# K-loops: deleted the 20 compiler-inserted s_waitcnt lgkmcnt(0) after the segment barriers (already waited by the inline-asm lgkmcnt(0) before the barrier)
# speedup vs baseline: 1.0155x; 1.0000x over previous
.LBB0_207:
	ds_read_b128 v[156:159], v152
	ds_read_b128 v[160:163], v152 offset:1024
	ds_read_b128 v[164:167], v152 offset:2048
	ds_read_b128 v[168:171], v152 offset:3072
	ds_read_b128 v[172:175], v153
	ds_read_b128 v[176:179], v153 offset:1024
	ds_read_b128 v[180:183], v153 offset:2048
	ds_read_b128 v[184:187], v153 offset:3072
	s_add_u32 s36, s0, 0xfffe0080
	s_addc_u32 s37, s1, -1
	s_cmp_eq_u32 s62, 4
	s_cselect_b32 s39, s25, s37
	s_cselect_b32 s38, s27, s36
	s_cselect_b32 s37, s29, s61
	s_cselect_b32 s36, s28, s60
	v_lshl_add_u64 v[146:147], s[0:1], 0, v[138:139]
	s_add_i32 m0, s35, 0xc000
	ds_read_b128 v[188:191], v154
	ds_read_b128 v[192:195], v154 offset:1024
	ds_read_b128 v[196:199], v154 offset:2048
	ds_read_b128 v[200:203], v154 offset:3072
	ds_read_b128 v[204:207], v154 offset:4096
	ds_read_b128 v[208:211], v154 offset:5120
	ds_read_b128 v[212:215], v154 offset:6144
	ds_read_b128 v[216:219], v154 offset:7168
	global_load_lds_dwordx4 v[146:147], off
	v_lshl_add_u64 v[146:147], s[0:1], 0, v[140:141]
	s_add_i32 m0, s35, 0xe000
	s_nop 0
	global_load_lds_dwordx4 v[146:147], off
	s_waitcnt vmcnt(8)
	s_waitcnt lgkmcnt(0)
	s_barrier
	s_setprio 1

	v_mfma_f32_16x16x32_bf16 v[126:129], v[156:159], v[188:191], v[126:129]
	v_mfma_f32_16x16x32_bf16 v[122:125], v[164:167], v[188:191], v[122:125]
	v_mfma_f32_16x16x32_bf16 v[118:121], v[156:159], v[196:199], v[118:121]
	v_mfma_f32_16x16x32_bf16 v[110:113], v[164:167], v[196:199], v[110:113]
	v_mfma_f32_16x16x32_bf16 v[102:105], v[156:159], v[204:207], v[102:105]
	v_mfma_f32_16x16x32_bf16 v[94:97], v[164:167], v[204:207], v[94:97]
	v_mfma_f32_16x16x32_bf16 v[86:89], v[156:159], v[212:215], v[86:89]
	v_mfma_f32_16x16x32_bf16 v[78:81], v[164:167], v[212:215], v[78:81]
	v_mfma_f32_16x16x32_bf16 v[126:129], v[160:163], v[192:195], v[126:129]
	v_mfma_f32_16x16x32_bf16 v[122:125], v[168:171], v[192:195], v[122:125]
	v_mfma_f32_16x16x32_bf16 v[118:121], v[160:163], v[200:203], v[118:121]
	v_mfma_f32_16x16x32_bf16 v[110:113], v[168:171], v[200:203], v[110:113]
	v_mfma_f32_16x16x32_bf16 v[102:105], v[160:163], v[208:211], v[102:105]
	v_mfma_f32_16x16x32_bf16 v[94:97], v[168:171], v[208:211], v[94:97]
	v_mfma_f32_16x16x32_bf16 v[86:89], v[160:163], v[216:219], v[86:89]
	v_mfma_f32_16x16x32_bf16 v[78:81], v[168:171], v[216:219], v[78:81]
	s_setprio 0
	s_setprio 1
	v_mfma_f32_16x16x32_bf16 v[114:117], v[172:175], v[188:191], v[114:117]
	v_mfma_f32_16x16x32_bf16 v[106:109], v[180:183], v[188:191], v[106:109]
	v_mfma_f32_16x16x32_bf16 v[98:101], v[172:175], v[196:199], v[98:101]
	v_mfma_f32_16x16x32_bf16 v[90:93], v[180:183], v[196:199], v[90:93]
	v_mfma_f32_16x16x32_bf16 v[82:85], v[172:175], v[204:207], v[82:85]
	v_mfma_f32_16x16x32_bf16 v[74:77], v[180:183], v[204:207], v[74:77]
	v_mfma_f32_16x16x32_bf16 v[70:73], v[172:175], v[212:215], v[70:73]
	v_mfma_f32_16x16x32_bf16 v[66:69], v[180:183], v[212:215], v[66:69]
	v_mfma_f32_16x16x32_bf16 v[114:117], v[176:179], v[192:195], v[114:117]
	v_mfma_f32_16x16x32_bf16 v[106:109], v[184:187], v[192:195], v[106:109]
	v_mfma_f32_16x16x32_bf16 v[98:101], v[176:179], v[200:203], v[98:101]
	v_mfma_f32_16x16x32_bf16 v[90:93], v[184:187], v[200:203], v[90:93]
	v_mfma_f32_16x16x32_bf16 v[82:85], v[176:179], v[208:211], v[82:85]
	v_mfma_f32_16x16x32_bf16 v[74:77], v[184:187], v[208:211], v[74:77]
	v_mfma_f32_16x16x32_bf16 v[70:73], v[176:179], v[216:219], v[70:73]
	v_mfma_f32_16x16x32_bf16 v[66:69], v[184:187], v[216:219], v[66:69]
	s_setprio 0
	s_barrier
	s_add_i32 s63, s53, s43
	v_lshl_add_u64 v[146:147], s[36:37], 0, v[132:133]
	s_mov_b32 m0, s63
	ds_read_b128 v[188:191], v154 offset:16384
	ds_read_b128 v[192:195], v154 offset:17408
	ds_read_b128 v[196:199], v154 offset:18432
	ds_read_b128 v[200:203], v154 offset:19456
	ds_read_b128 v[204:207], v154 offset:20480
	ds_read_b128 v[208:211], v154 offset:21504
	ds_read_b128 v[212:215], v154 offset:22528
	ds_read_b128 v[216:219], v154 offset:23552
	global_load_lds_dwordx4 v[146:147], off
	s_add_i32 m0, s63, 0x2000
	s_add_u32 s64, s36, 0x80000
	v_lshl_add_u64 v[220:221], s[36:37], 0, v[136:137]
	s_addc_u32 s65, s37, 0
	s_add_i32 s63, s54, s43
	global_load_lds_dwordx4 v[220:221], off
	v_lshl_add_u64 v[222:223], s[64:65], 0, v[132:133]
	s_mov_b32 m0, s63
	v_lshl_add_u64 v[224:225], s[38:39], 0, v[134:135]
	global_load_lds_dwordx4 v[222:223], off
	v_lshl_add_u64 v[222:223], s[64:65], 0, v[136:137]
	s_add_i32 m0, s63, 0x2000
	s_nop 0
	global_load_lds_dwordx4 v[222:223], off
	v_lshl_add_u64 v[222:223], s[38:39], 0, v[130:131]
	s_mov_b32 m0, s35
	s_nop 0
	global_load_lds_dwordx4 v[222:223], off
	s_mov_b32 m0, s46
	s_nop 0
	global_load_lds_dwordx4 v[224:225], off
	s_waitcnt vmcnt(8)
	s_waitcnt lgkmcnt(0)
	s_barrier
	s_setprio 1

	v_mfma_f32_16x16x32_bf16 v[62:65], v[156:159], v[188:191], v[62:65]
	v_mfma_f32_16x16x32_bf16 v[58:61], v[164:167], v[188:191], v[58:61]
	v_mfma_f32_16x16x32_bf16 v[54:57], v[156:159], v[196:199], v[54:57]
	v_mfma_f32_16x16x32_bf16 v[46:49], v[164:167], v[196:199], v[46:49]
	v_mfma_f32_16x16x32_bf16 v[38:41], v[156:159], v[204:207], v[38:41]
	v_mfma_f32_16x16x32_bf16 v[30:33], v[164:167], v[204:207], v[30:33]
	v_mfma_f32_16x16x32_bf16 v[22:25], v[156:159], v[212:215], v[22:25]
	v_mfma_f32_16x16x32_bf16 v[14:17], v[164:167], v[212:215], v[14:17]
	v_mfma_f32_16x16x32_bf16 v[62:65], v[160:163], v[192:195], v[62:65]
	v_mfma_f32_16x16x32_bf16 v[58:61], v[168:171], v[192:195], v[58:61]
	v_mfma_f32_16x16x32_bf16 v[54:57], v[160:163], v[200:203], v[54:57]
	v_mfma_f32_16x16x32_bf16 v[46:49], v[168:171], v[200:203], v[46:49]
	v_mfma_f32_16x16x32_bf16 v[38:41], v[160:163], v[208:211], v[38:41]
	v_mfma_f32_16x16x32_bf16 v[30:33], v[168:171], v[208:211], v[30:33]
	v_mfma_f32_16x16x32_bf16 v[22:25], v[160:163], v[216:219], v[22:25]
	v_mfma_f32_16x16x32_bf16 v[14:17], v[168:171], v[216:219], v[14:17]
	s_setprio 0
	s_setprio 1
	v_mfma_f32_16x16x32_bf16 v[50:53], v[172:175], v[188:191], v[50:53]
	v_mfma_f32_16x16x32_bf16 v[42:45], v[180:183], v[188:191], v[42:45]
	v_mfma_f32_16x16x32_bf16 v[34:37], v[172:175], v[196:199], v[34:37]
	v_mfma_f32_16x16x32_bf16 v[26:29], v[180:183], v[196:199], v[26:29]
	v_mfma_f32_16x16x32_bf16 v[18:21], v[172:175], v[204:207], v[18:21]
	v_mfma_f32_16x16x32_bf16 v[10:13], v[180:183], v[204:207], v[10:13]
	v_mfma_f32_16x16x32_bf16 v[6:9], v[172:175], v[212:215], v[6:9]
	v_mfma_f32_16x16x32_bf16 v[2:5], v[180:183], v[212:215], v[2:5]
	v_mfma_f32_16x16x32_bf16 v[50:53], v[176:179], v[192:195], v[50:53]
	v_mfma_f32_16x16x32_bf16 v[42:45], v[184:187], v[192:195], v[42:45]
	v_mfma_f32_16x16x32_bf16 v[34:37], v[176:179], v[200:203], v[34:37]
	v_mfma_f32_16x16x32_bf16 v[26:29], v[184:187], v[200:203], v[26:29]
	v_mfma_f32_16x16x32_bf16 v[18:21], v[176:179], v[208:211], v[18:21]
	v_mfma_f32_16x16x32_bf16 v[10:13], v[184:187], v[208:211], v[10:13]
	v_mfma_f32_16x16x32_bf16 v[6:9], v[176:179], v[216:219], v[6:9]
	v_mfma_f32_16x16x32_bf16 v[2:5], v[184:187], v[216:219], v[2:5]
	s_setprio 0
	s_barrier
	s_add_i32 s63, 0, 0x18000
	v_add_u32_e32 v155, s63, v150
	s_add_i32 s64, 0, 0x1c000
	ds_read_b128 v[156:159], v155
	ds_read_b128 v[160:163], v155 offset:1024
	ds_read_b128 v[164:167], v155 offset:2048
	ds_read_b128 v[168:171], v155 offset:3072
	v_add_u32_e32 v155, s64, v150
	ds_read_b128 v[172:175], v155
	ds_read_b128 v[176:179], v155 offset:1024
	ds_read_b128 v[180:183], v155 offset:2048
	ds_read_b128 v[184:187], v155 offset:3072
	s_add_u32 s38, s38, 0x20000
	s_addc_u32 s39, s39, 0
	s_mov_b32 m0, s47
	v_lshl_add_u64 v[226:227], s[38:39], 0, v[130:131]
	ds_read_b128 v[188:191], v154 offset:32768
	ds_read_b128 v[192:195], v154 offset:33792
	ds_read_b128 v[196:199], v154 offset:34816
	ds_read_b128 v[200:203], v154 offset:35840
	ds_read_b128 v[204:207], v154 offset:36864
	ds_read_b128 v[208:211], v154 offset:37888
	ds_read_b128 v[212:215], v154 offset:38912
	ds_read_b128 v[216:219], v154 offset:39936
	global_load_lds_dwordx4 v[226:227], off
	v_lshl_add_u64 v[226:227], s[38:39], 0, v[134:135]
	s_mov_b32 m0, s48
	s_nop 0
	global_load_lds_dwordx4 v[226:227], off
	s_waitcnt vmcnt(8)
	s_waitcnt lgkmcnt(0)
	s_barrier
	s_setprio 1

	v_mfma_f32_16x16x32_bf16 v[126:129], v[156:159], v[188:191], v[126:129]
	v_mfma_f32_16x16x32_bf16 v[122:125], v[164:167], v[188:191], v[122:125]
	v_mfma_f32_16x16x32_bf16 v[118:121], v[156:159], v[196:199], v[118:121]
	v_mfma_f32_16x16x32_bf16 v[110:113], v[164:167], v[196:199], v[110:113]
	v_mfma_f32_16x16x32_bf16 v[102:105], v[156:159], v[204:207], v[102:105]
	v_mfma_f32_16x16x32_bf16 v[94:97], v[164:167], v[204:207], v[94:97]
	v_mfma_f32_16x16x32_bf16 v[86:89], v[156:159], v[212:215], v[86:89]
	v_mfma_f32_16x16x32_bf16 v[78:81], v[164:167], v[212:215], v[78:81]
	v_mfma_f32_16x16x32_bf16 v[126:129], v[160:163], v[192:195], v[126:129]
	v_mfma_f32_16x16x32_bf16 v[122:125], v[168:171], v[192:195], v[122:125]
	v_mfma_f32_16x16x32_bf16 v[118:121], v[160:163], v[200:203], v[118:121]
	v_mfma_f32_16x16x32_bf16 v[110:113], v[168:171], v[200:203], v[110:113]
	v_mfma_f32_16x16x32_bf16 v[102:105], v[160:163], v[208:211], v[102:105]
	v_mfma_f32_16x16x32_bf16 v[94:97], v[168:171], v[208:211], v[94:97]
	v_mfma_f32_16x16x32_bf16 v[86:89], v[160:163], v[216:219], v[86:89]
	v_mfma_f32_16x16x32_bf16 v[78:81], v[168:171], v[216:219], v[78:81]
	s_setprio 0
	s_setprio 1
	v_mfma_f32_16x16x32_bf16 v[114:117], v[172:175], v[188:191], v[114:117]
	v_mfma_f32_16x16x32_bf16 v[106:109], v[180:183], v[188:191], v[106:109]
	v_mfma_f32_16x16x32_bf16 v[98:101], v[172:175], v[196:199], v[98:101]
	v_mfma_f32_16x16x32_bf16 v[90:93], v[180:183], v[196:199], v[90:93]
	v_mfma_f32_16x16x32_bf16 v[82:85], v[172:175], v[204:207], v[82:85]
	v_mfma_f32_16x16x32_bf16 v[74:77], v[180:183], v[204:207], v[74:77]
	v_mfma_f32_16x16x32_bf16 v[70:73], v[172:175], v[212:215], v[70:73]
	v_mfma_f32_16x16x32_bf16 v[66:69], v[180:183], v[212:215], v[66:69]
	v_mfma_f32_16x16x32_bf16 v[114:117], v[176:179], v[192:195], v[114:117]
	v_mfma_f32_16x16x32_bf16 v[106:109], v[184:187], v[192:195], v[106:109]
	v_mfma_f32_16x16x32_bf16 v[98:101], v[176:179], v[200:203], v[98:101]
	v_mfma_f32_16x16x32_bf16 v[90:93], v[184:187], v[200:203], v[90:93]
	v_mfma_f32_16x16x32_bf16 v[82:85], v[176:179], v[208:211], v[82:85]
	v_mfma_f32_16x16x32_bf16 v[74:77], v[184:187], v[208:211], v[74:77]
	v_mfma_f32_16x16x32_bf16 v[70:73], v[176:179], v[216:219], v[70:73]
	v_mfma_f32_16x16x32_bf16 v[66:69], v[184:187], v[216:219], v[66:69]
	s_setprio 0
	s_barrier
	s_add_i32 s38, s63, s43
	v_lshl_add_u64 v[146:147], v[146:147], 0, s[8:9]
	s_mov_b32 m0, s38
	ds_read_b128 v[188:191], v154 offset:49152
	ds_read_b128 v[192:195], v154 offset:50176
	ds_read_b128 v[196:199], v154 offset:51200
	ds_read_b128 v[200:203], v154 offset:52224
	ds_read_b128 v[204:207], v154 offset:53248
	ds_read_b128 v[208:211], v154 offset:54272
	ds_read_b128 v[212:215], v154 offset:55296
	ds_read_b128 v[216:219], v154 offset:56320
	global_load_lds_dwordx4 v[146:147], off
	s_add_i32 m0, s38, 0x2000
	s_add_u32 s36, s36, 0x80080
	v_lshl_add_u64 v[146:147], v[220:221], 0, s[8:9]
	s_addc_u32 s37, s37, 0
	s_add_i32 s38, s64, s43
	global_load_lds_dwordx4 v[146:147], off
	v_lshl_add_u64 v[146:147], s[36:37], 0, v[132:133]
	s_mov_b32 m0, s38
	s_nop 0
	global_load_lds_dwordx4 v[146:147], off
	v_lshl_add_u64 v[146:147], s[36:37], 0, v[136:137]
	s_add_i32 m0, s38, 0x2000
	s_nop 0
	global_load_lds_dwordx4 v[146:147], off
	v_lshl_add_u64 v[146:147], v[222:223], 0, s[8:9]
	s_mov_b32 m0, s50
	s_nop 0
	global_load_lds_dwordx4 v[146:147], off
	v_lshl_add_u64 v[146:147], v[224:225], 0, s[8:9]
	s_mov_b32 m0, s51
	s_nop 0
	global_load_lds_dwordx4 v[146:147], off
	s_waitcnt vmcnt(8)
	s_waitcnt lgkmcnt(0)
	s_barrier
	s_setprio 1

	v_mfma_f32_16x16x32_bf16 v[62:65], v[156:159], v[188:191], v[62:65]
	v_mfma_f32_16x16x32_bf16 v[58:61], v[164:167], v[188:191], v[58:61]
	v_mfma_f32_16x16x32_bf16 v[54:57], v[156:159], v[196:199], v[54:57]
	v_mfma_f32_16x16x32_bf16 v[46:49], v[164:167], v[196:199], v[46:49]
	v_mfma_f32_16x16x32_bf16 v[38:41], v[156:159], v[204:207], v[38:41]
	v_mfma_f32_16x16x32_bf16 v[30:33], v[164:167], v[204:207], v[30:33]
	v_mfma_f32_16x16x32_bf16 v[22:25], v[156:159], v[212:215], v[22:25]
	v_mfma_f32_16x16x32_bf16 v[14:17], v[164:167], v[212:215], v[14:17]
	v_mfma_f32_16x16x32_bf16 v[62:65], v[160:163], v[192:195], v[62:65]
	v_mfma_f32_16x16x32_bf16 v[58:61], v[168:171], v[192:195], v[58:61]
	v_mfma_f32_16x16x32_bf16 v[54:57], v[160:163], v[200:203], v[54:57]
	v_mfma_f32_16x16x32_bf16 v[46:49], v[168:171], v[200:203], v[46:49]
	v_mfma_f32_16x16x32_bf16 v[38:41], v[160:163], v[208:211], v[38:41]
	v_mfma_f32_16x16x32_bf16 v[30:33], v[168:171], v[208:211], v[30:33]
	v_mfma_f32_16x16x32_bf16 v[22:25], v[160:163], v[216:219], v[22:25]
	v_mfma_f32_16x16x32_bf16 v[14:17], v[168:171], v[216:219], v[14:17]
	s_setprio 0
	s_setprio 1
	v_mfma_f32_16x16x32_bf16 v[50:53], v[172:175], v[188:191], v[50:53]
	v_mfma_f32_16x16x32_bf16 v[42:45], v[180:183], v[188:191], v[42:45]
	v_mfma_f32_16x16x32_bf16 v[34:37], v[172:175], v[196:199], v[34:37]
	v_mfma_f32_16x16x32_bf16 v[26:29], v[180:183], v[196:199], v[26:29]
	v_mfma_f32_16x16x32_bf16 v[18:21], v[172:175], v[204:207], v[18:21]
	v_mfma_f32_16x16x32_bf16 v[10:13], v[180:183], v[204:207], v[10:13]
	v_mfma_f32_16x16x32_bf16 v[6:9], v[172:175], v[212:215], v[6:9]
	v_mfma_f32_16x16x32_bf16 v[2:5], v[180:183], v[212:215], v[2:5]
	v_mfma_f32_16x16x32_bf16 v[50:53], v[176:179], v[192:195], v[50:53]
	v_mfma_f32_16x16x32_bf16 v[42:45], v[184:187], v[192:195], v[42:45]
	v_mfma_f32_16x16x32_bf16 v[34:37], v[176:179], v[200:203], v[34:37]
	v_mfma_f32_16x16x32_bf16 v[26:29], v[184:187], v[200:203], v[26:29]
	v_mfma_f32_16x16x32_bf16 v[18:21], v[176:179], v[208:211], v[18:21]
	v_mfma_f32_16x16x32_bf16 v[10:13], v[184:187], v[208:211], v[10:13]
	v_mfma_f32_16x16x32_bf16 v[6:9], v[176:179], v[216:219], v[6:9]
	v_mfma_f32_16x16x32_bf16 v[2:5], v[184:187], v[216:219], v[2:5]
	s_setprio 0
	s_barrier
	s_add_i32 s62, s62, 2
	s_add_u32 s0, s0, 0x100
	s_addc_u32 s1, s1, 0
	s_add_u32 s60, s60, 0x100
	s_addc_u32 s61, s61, 0
	s_cmp_gt_u32 s62, 5
	s_cbranch_scc0 .LBB0_207
	s_and_b64 vcc, exec, s[10:11]
	s_cbranch_vccz .LBB0_210
	s_barrier

.LBB0_290:
	s_add_u32 s12, s60, s10
	s_addc_u32 s13, s61, s11
	s_add_u32 s12, s12, 0x100
	s_addc_u32 s13, s13, 0
	s_add_u32 s97, s28, s10
	s_addc_u32 vcc_lo, s29, s11
	s_add_i32 vcc_hi, 0, 0x10000
	s_cmpk_eq_i32 s10, 0xf00
	s_cselect_b32 s41, s63, s13
	s_cselect_b32 s40, s94, s12
	v_add_u32_e32 v154, vcc_hi, v169
	s_cselect_b32 s13, s67, vcc_lo
	s_cselect_b32 s12, s95, s97
	s_add_i32 s97, 0, 0x14000
	ds_read_b128 v[146:149], v154
	ds_read_b128 v[150:153], v154 offset:1024
	ds_read_b128 v[164:167], v154 offset:2048
	ds_read_b128 v[172:175], v154 offset:3072
	v_add_u32_e32 v154, s97, v169
	ds_read_b128 v[176:179], v154
	ds_read_b128 v[180:183], v154 offset:1024
	ds_read_b128 v[184:187], v154 offset:2048
	ds_read_b128 v[188:191], v154 offset:3072
	v_lshl_add_u64 v[196:197], v[142:143], 0, s[10:11]
	s_add_i32 m0, s81, 0xc000
	ds_read_b128 v[200:203], v171
	ds_read_b128 v[204:207], v171 offset:1024
	ds_read_b128 v[208:211], v171 offset:2048
	ds_read_b128 v[212:215], v171 offset:3072
	ds_read_b128 v[216:219], v171 offset:4096
	ds_read_b128 v[220:223], v171 offset:5120
	ds_read_b128 v[224:227], v171 offset:6144
	ds_read_b128 v[228:231], v171 offset:7168
	global_load_lds_dwordx4 v[196:197], off
	v_lshl_add_u64 v[196:197], v[144:145], 0, s[10:11]
	s_add_i32 m0, s81, 0xe000
	s_nop 0
	global_load_lds_dwordx4 v[196:197], off
	s_waitcnt vmcnt(8)
	s_waitcnt lgkmcnt(0)
	s_barrier
	s_setprio 1

	v_mfma_f32_16x16x32_bf16 v[126:129], v[146:149], v[200:203], v[126:129]
	v_mfma_f32_16x16x32_bf16 v[122:125], v[164:167], v[200:203], v[122:125]
	v_mfma_f32_16x16x32_bf16 v[118:121], v[146:149], v[208:211], v[118:121]
	v_mfma_f32_16x16x32_bf16 v[114:117], v[164:167], v[208:211], v[114:117]
	v_mfma_f32_16x16x32_bf16 v[110:113], v[146:149], v[216:219], v[110:113]
	v_mfma_f32_16x16x32_bf16 v[106:109], v[164:167], v[216:219], v[106:109]
	v_mfma_f32_16x16x32_bf16 v[102:105], v[146:149], v[224:227], v[102:105]
	v_mfma_f32_16x16x32_bf16 v[98:101], v[164:167], v[224:227], v[98:101]
	v_mfma_f32_16x16x32_bf16 v[126:129], v[150:153], v[204:207], v[126:129]
	v_mfma_f32_16x16x32_bf16 v[122:125], v[172:175], v[204:207], v[122:125]
	v_mfma_f32_16x16x32_bf16 v[118:121], v[150:153], v[212:215], v[118:121]
	v_mfma_f32_16x16x32_bf16 v[114:117], v[172:175], v[212:215], v[114:117]
	v_mfma_f32_16x16x32_bf16 v[110:113], v[150:153], v[220:223], v[110:113]
	v_mfma_f32_16x16x32_bf16 v[106:109], v[172:175], v[220:223], v[106:109]
	v_mfma_f32_16x16x32_bf16 v[102:105], v[150:153], v[228:231], v[102:105]
	v_mfma_f32_16x16x32_bf16 v[98:101], v[172:175], v[228:231], v[98:101]
	s_setprio 0
	s_setprio 1
	v_mfma_f32_16x16x32_bf16 v[94:97], v[176:179], v[200:203], v[94:97]
	v_mfma_f32_16x16x32_bf16 v[90:93], v[184:187], v[200:203], v[90:93]
	v_mfma_f32_16x16x32_bf16 v[86:89], v[176:179], v[208:211], v[86:89]
	v_mfma_f32_16x16x32_bf16 v[82:85], v[184:187], v[208:211], v[82:85]
	v_mfma_f32_16x16x32_bf16 v[78:81], v[176:179], v[216:219], v[78:81]
	v_mfma_f32_16x16x32_bf16 v[74:77], v[184:187], v[216:219], v[74:77]
	v_mfma_f32_16x16x32_bf16 v[70:73], v[176:179], v[224:227], v[70:73]
	v_mfma_f32_16x16x32_bf16 v[66:69], v[184:187], v[224:227], v[66:69]
	v_mfma_f32_16x16x32_bf16 v[94:97], v[180:183], v[204:207], v[94:97]
	v_mfma_f32_16x16x32_bf16 v[90:93], v[188:191], v[204:207], v[90:93]
	v_mfma_f32_16x16x32_bf16 v[86:89], v[180:183], v[212:215], v[86:89]
	v_mfma_f32_16x16x32_bf16 v[82:85], v[188:191], v[212:215], v[82:85]
	v_mfma_f32_16x16x32_bf16 v[78:81], v[180:183], v[220:223], v[78:81]
	v_mfma_f32_16x16x32_bf16 v[74:77], v[188:191], v[220:223], v[74:77]
	v_mfma_f32_16x16x32_bf16 v[70:73], v[180:183], v[228:231], v[70:73]
	v_mfma_f32_16x16x32_bf16 v[66:69], v[188:191], v[228:231], v[66:69]
	s_setprio 0
	s_barrier
	s_add_i32 vcc_lo, vcc_hi, s80
	v_lshl_add_u64 v[196:197], s[12:13], 0, v[132:133]
	s_mov_b32 m0, vcc_lo
	ds_read_b128 v[200:203], v171 offset:16384
	ds_read_b128 v[204:207], v171 offset:17408
	ds_read_b128 v[208:211], v171 offset:18432
	ds_read_b128 v[212:215], v171 offset:19456
	ds_read_b128 v[216:219], v171 offset:20480
	ds_read_b128 v[220:223], v171 offset:21504
	ds_read_b128 v[224:227], v171 offset:22528
	ds_read_b128 v[228:231], v171 offset:23552
	global_load_lds_dwordx4 v[196:197], off
	s_add_i32 m0, vcc_lo, 0x2000
	s_add_u32 vcc_lo, s12, 0x80000
	v_lshl_add_u64 v[232:233], s[12:13], 0, v[136:137]
	s_addc_u32 vcc_hi, s13, 0
	s_add_i32 s97, s97, s80
	global_load_lds_dwordx4 v[232:233], off
	v_lshl_add_u64 v[234:235], vcc, 0, v[132:133]
	s_mov_b32 m0, s97
	v_lshl_add_u64 v[236:237], s[40:41], 0, v[134:135]
	global_load_lds_dwordx4 v[234:235], off
	v_lshl_add_u64 v[234:235], vcc, 0, v[136:137]
	s_add_i32 m0, s97, 0x2000
	s_nop 0
	global_load_lds_dwordx4 v[234:235], off
	v_lshl_add_u64 v[234:235], s[40:41], 0, v[130:131]
	s_mov_b32 m0, s81
	s_nop 0
	global_load_lds_dwordx4 v[234:235], off
	s_mov_b32 m0, s82
	s_nop 0
	global_load_lds_dwordx4 v[236:237], off
	s_waitcnt vmcnt(8)
	s_waitcnt lgkmcnt(0)
	s_barrier
	s_setprio 1

	v_mfma_f32_16x16x32_bf16 v[62:65], v[146:149], v[200:203], v[62:65]
	v_mfma_f32_16x16x32_bf16 v[58:61], v[164:167], v[200:203], v[58:61]
	v_mfma_f32_16x16x32_bf16 v[54:57], v[146:149], v[208:211], v[54:57]
	v_mfma_f32_16x16x32_bf16 v[50:53], v[164:167], v[208:211], v[50:53]
	v_mfma_f32_16x16x32_bf16 v[46:49], v[146:149], v[216:219], v[46:49]
	v_mfma_f32_16x16x32_bf16 v[42:45], v[164:167], v[216:219], v[42:45]
	v_mfma_f32_16x16x32_bf16 v[38:41], v[146:149], v[224:227], v[38:41]
	v_mfma_f32_16x16x32_bf16 v[34:37], v[164:167], v[224:227], v[34:37]
	v_mfma_f32_16x16x32_bf16 v[62:65], v[150:153], v[204:207], v[62:65]
	v_mfma_f32_16x16x32_bf16 v[58:61], v[172:175], v[204:207], v[58:61]
	v_mfma_f32_16x16x32_bf16 v[54:57], v[150:153], v[212:215], v[54:57]
	v_mfma_f32_16x16x32_bf16 v[50:53], v[172:175], v[212:215], v[50:53]
	v_mfma_f32_16x16x32_bf16 v[46:49], v[150:153], v[220:223], v[46:49]
	v_mfma_f32_16x16x32_bf16 v[42:45], v[172:175], v[220:223], v[42:45]
	v_mfma_f32_16x16x32_bf16 v[38:41], v[150:153], v[228:231], v[38:41]
	v_mfma_f32_16x16x32_bf16 v[34:37], v[172:175], v[228:231], v[34:37]
	s_setprio 0
	s_setprio 1
	v_mfma_f32_16x16x32_bf16 v[30:33], v[176:179], v[200:203], v[30:33]
	v_mfma_f32_16x16x32_bf16 v[26:29], v[184:187], v[200:203], v[26:29]
	v_mfma_f32_16x16x32_bf16 v[22:25], v[176:179], v[208:211], v[22:25]
	v_mfma_f32_16x16x32_bf16 v[18:21], v[184:187], v[208:211], v[18:21]
	v_mfma_f32_16x16x32_bf16 v[14:17], v[176:179], v[216:219], v[14:17]
	v_mfma_f32_16x16x32_bf16 v[10:13], v[184:187], v[216:219], v[10:13]
	v_mfma_f32_16x16x32_bf16 v[6:9], v[176:179], v[224:227], v[6:9]
	v_mfma_f32_16x16x32_bf16 v[2:5], v[184:187], v[224:227], v[2:5]
	v_mfma_f32_16x16x32_bf16 v[30:33], v[180:183], v[204:207], v[30:33]
	v_mfma_f32_16x16x32_bf16 v[26:29], v[188:191], v[204:207], v[26:29]
	v_mfma_f32_16x16x32_bf16 v[22:25], v[180:183], v[212:215], v[22:25]
	v_mfma_f32_16x16x32_bf16 v[18:21], v[188:191], v[212:215], v[18:21]
	v_mfma_f32_16x16x32_bf16 v[14:17], v[180:183], v[220:223], v[14:17]
	v_mfma_f32_16x16x32_bf16 v[10:13], v[188:191], v[220:223], v[10:13]
	v_mfma_f32_16x16x32_bf16 v[6:9], v[180:183], v[228:231], v[6:9]
	v_mfma_f32_16x16x32_bf16 v[2:5], v[188:191], v[228:231], v[2:5]
	s_setprio 0
	s_barrier
	s_add_i32 s97, 0, 0x18000
	v_add_u32_e32 v154, s97, v169
	s_add_i32 vcc_lo, 0, 0x1c000
	ds_read_b128 v[146:149], v154
	ds_read_b128 v[150:153], v154 offset:1024
	ds_read_b128 v[164:167], v154 offset:2048
	ds_read_b128 v[172:175], v154 offset:3072
	v_add_u32_e32 v154, vcc_lo, v169
	ds_read_b128 v[176:179], v154
	ds_read_b128 v[180:183], v154 offset:1024
	ds_read_b128 v[184:187], v154 offset:2048
	ds_read_b128 v[188:191], v154 offset:3072
	s_add_u32 s40, s40, 0x80000
	s_addc_u32 s41, s41, 0
	s_mov_b32 m0, s83
	v_lshl_add_u64 v[238:239], s[40:41], 0, v[130:131]
	ds_read_b128 v[200:203], v171 offset:32768
	ds_read_b128 v[204:207], v171 offset:33792
	ds_read_b128 v[208:211], v171 offset:34816
	ds_read_b128 v[212:215], v171 offset:35840
	ds_read_b128 v[216:219], v171 offset:36864
	ds_read_b128 v[220:223], v171 offset:37888
	ds_read_b128 v[224:227], v171 offset:38912
	ds_read_b128 v[228:231], v171 offset:39936
	global_load_lds_dwordx4 v[238:239], off
	v_lshl_add_u64 v[238:239], s[40:41], 0, v[134:135]
	s_mov_b32 m0, s84
	s_nop 0
	global_load_lds_dwordx4 v[238:239], off
	s_waitcnt vmcnt(8)
	s_waitcnt lgkmcnt(0)
	s_barrier
	s_setprio 1

	v_mfma_f32_16x16x32_bf16 v[126:129], v[146:149], v[200:203], v[126:129]
	v_mfma_f32_16x16x32_bf16 v[122:125], v[164:167], v[200:203], v[122:125]
	v_mfma_f32_16x16x32_bf16 v[118:121], v[146:149], v[208:211], v[118:121]
	v_mfma_f32_16x16x32_bf16 v[114:117], v[164:167], v[208:211], v[114:117]
	v_mfma_f32_16x16x32_bf16 v[110:113], v[146:149], v[216:219], v[110:113]
	v_mfma_f32_16x16x32_bf16 v[106:109], v[164:167], v[216:219], v[106:109]
	v_mfma_f32_16x16x32_bf16 v[102:105], v[146:149], v[224:227], v[102:105]
	v_mfma_f32_16x16x32_bf16 v[98:101], v[164:167], v[224:227], v[98:101]
	v_mfma_f32_16x16x32_bf16 v[126:129], v[150:153], v[204:207], v[126:129]
	v_mfma_f32_16x16x32_bf16 v[122:125], v[172:175], v[204:207], v[122:125]
	v_mfma_f32_16x16x32_bf16 v[118:121], v[150:153], v[212:215], v[118:121]
	v_mfma_f32_16x16x32_bf16 v[114:117], v[172:175], v[212:215], v[114:117]
	v_mfma_f32_16x16x32_bf16 v[110:113], v[150:153], v[220:223], v[110:113]
	v_mfma_f32_16x16x32_bf16 v[106:109], v[172:175], v[220:223], v[106:109]
	v_mfma_f32_16x16x32_bf16 v[102:105], v[150:153], v[228:231], v[102:105]
	v_mfma_f32_16x16x32_bf16 v[98:101], v[172:175], v[228:231], v[98:101]
	s_setprio 0
	s_setprio 1
	v_mfma_f32_16x16x32_bf16 v[94:97], v[176:179], v[200:203], v[94:97]
	v_mfma_f32_16x16x32_bf16 v[90:93], v[184:187], v[200:203], v[90:93]
	v_mfma_f32_16x16x32_bf16 v[86:89], v[176:179], v[208:211], v[86:89]
	v_mfma_f32_16x16x32_bf16 v[82:85], v[184:187], v[208:211], v[82:85]
	v_mfma_f32_16x16x32_bf16 v[78:81], v[176:179], v[216:219], v[78:81]
	v_mfma_f32_16x16x32_bf16 v[74:77], v[184:187], v[216:219], v[74:77]
	v_mfma_f32_16x16x32_bf16 v[70:73], v[176:179], v[224:227], v[70:73]
	v_mfma_f32_16x16x32_bf16 v[66:69], v[184:187], v[224:227], v[66:69]
	v_mfma_f32_16x16x32_bf16 v[94:97], v[180:183], v[204:207], v[94:97]
	v_mfma_f32_16x16x32_bf16 v[90:93], v[188:191], v[204:207], v[90:93]
	v_mfma_f32_16x16x32_bf16 v[86:89], v[180:183], v[212:215], v[86:89]
	v_mfma_f32_16x16x32_bf16 v[82:85], v[188:191], v[212:215], v[82:85]
	v_mfma_f32_16x16x32_bf16 v[78:81], v[180:183], v[220:223], v[78:81]
	v_mfma_f32_16x16x32_bf16 v[74:77], v[188:191], v[220:223], v[74:77]
	v_mfma_f32_16x16x32_bf16 v[70:73], v[180:183], v[228:231], v[70:73]
	v_mfma_f32_16x16x32_bf16 v[66:69], v[188:191], v[228:231], v[66:69]
	s_setprio 0
	s_barrier
	s_add_i32 s40, s97, s80
	v_lshl_add_u64 v[196:197], v[196:197], 0, s[34:35]
	s_mov_b32 m0, s40
	ds_read_b128 v[200:203], v171 offset:49152
	ds_read_b128 v[204:207], v171 offset:50176
	ds_read_b128 v[208:211], v171 offset:51200
	ds_read_b128 v[212:215], v171 offset:52224
	ds_read_b128 v[216:219], v171 offset:53248
	ds_read_b128 v[220:223], v171 offset:54272
	ds_read_b128 v[224:227], v171 offset:55296
	ds_read_b128 v[228:231], v171 offset:56320
	global_load_lds_dwordx4 v[196:197], off
	s_add_i32 m0, s40, 0x2000
	s_add_u32 s12, s12, 0x80080
	v_lshl_add_u64 v[196:197], v[232:233], 0, s[34:35]
	s_addc_u32 s13, s13, 0
	s_add_i32 s40, vcc_lo, s80
	global_load_lds_dwordx4 v[196:197], off
	v_lshl_add_u64 v[196:197], s[12:13], 0, v[132:133]
	s_mov_b32 m0, s40
	s_nop 0
	global_load_lds_dwordx4 v[196:197], off
	v_lshl_add_u64 v[196:197], s[12:13], 0, v[136:137]
	s_add_i32 m0, s40, 0x2000
	s_nop 0
	global_load_lds_dwordx4 v[196:197], off
	v_lshl_add_u64 v[196:197], v[234:235], 0, s[34:35]
	s_mov_b32 m0, s85
	s_nop 0
	global_load_lds_dwordx4 v[196:197], off
	v_lshl_add_u64 v[196:197], v[236:237], 0, s[34:35]
	s_mov_b32 m0, s86
	s_nop 0
	global_load_lds_dwordx4 v[196:197], off
	s_waitcnt vmcnt(8)
	s_waitcnt lgkmcnt(0)
	s_barrier
	s_setprio 1

	v_mfma_f32_16x16x32_bf16 v[62:65], v[146:149], v[200:203], v[62:65]
	v_mfma_f32_16x16x32_bf16 v[58:61], v[164:167], v[200:203], v[58:61]
	v_mfma_f32_16x16x32_bf16 v[54:57], v[146:149], v[208:211], v[54:57]
	v_mfma_f32_16x16x32_bf16 v[50:53], v[164:167], v[208:211], v[50:53]
	v_mfma_f32_16x16x32_bf16 v[46:49], v[146:149], v[216:219], v[46:49]
	v_mfma_f32_16x16x32_bf16 v[42:45], v[164:167], v[216:219], v[42:45]
	v_mfma_f32_16x16x32_bf16 v[38:41], v[146:149], v[224:227], v[38:41]
	v_mfma_f32_16x16x32_bf16 v[34:37], v[164:167], v[224:227], v[34:37]
	v_mfma_f32_16x16x32_bf16 v[62:65], v[150:153], v[204:207], v[62:65]
	v_mfma_f32_16x16x32_bf16 v[58:61], v[172:175], v[204:207], v[58:61]
	v_mfma_f32_16x16x32_bf16 v[54:57], v[150:153], v[212:215], v[54:57]
	v_mfma_f32_16x16x32_bf16 v[50:53], v[172:175], v[212:215], v[50:53]
	v_mfma_f32_16x16x32_bf16 v[46:49], v[150:153], v[220:223], v[46:49]
	v_mfma_f32_16x16x32_bf16 v[42:45], v[172:175], v[220:223], v[42:45]
	v_mfma_f32_16x16x32_bf16 v[38:41], v[150:153], v[228:231], v[38:41]
	v_mfma_f32_16x16x32_bf16 v[34:37], v[172:175], v[228:231], v[34:37]
	s_setprio 0
	s_setprio 1
	v_mfma_f32_16x16x32_bf16 v[30:33], v[176:179], v[200:203], v[30:33]
	v_mfma_f32_16x16x32_bf16 v[26:29], v[184:187], v[200:203], v[26:29]
	v_mfma_f32_16x16x32_bf16 v[22:25], v[176:179], v[208:211], v[22:25]
	v_mfma_f32_16x16x32_bf16 v[18:21], v[184:187], v[208:211], v[18:21]
	v_mfma_f32_16x16x32_bf16 v[14:17], v[176:179], v[216:219], v[14:17]
	v_mfma_f32_16x16x32_bf16 v[10:13], v[184:187], v[216:219], v[10:13]
	v_mfma_f32_16x16x32_bf16 v[6:9], v[176:179], v[224:227], v[6:9]
	v_mfma_f32_16x16x32_bf16 v[2:5], v[184:187], v[224:227], v[2:5]
	v_mfma_f32_16x16x32_bf16 v[30:33], v[180:183], v[204:207], v[30:33]
	v_mfma_f32_16x16x32_bf16 v[26:29], v[188:191], v[204:207], v[26:29]
	v_mfma_f32_16x16x32_bf16 v[22:25], v[180:183], v[212:215], v[22:25]
	v_mfma_f32_16x16x32_bf16 v[18:21], v[188:191], v[212:215], v[18:21]
	v_mfma_f32_16x16x32_bf16 v[14:17], v[180:183], v[220:223], v[14:17]
	v_mfma_f32_16x16x32_bf16 v[10:13], v[188:191], v[220:223], v[10:13]
	v_mfma_f32_16x16x32_bf16 v[6:9], v[180:183], v[228:231], v[6:9]
	v_mfma_f32_16x16x32_bf16 v[2:5], v[188:191], v[228:231], v[2:5]
	s_setprio 0
	s_barrier
	s_add_i32 s96, s96, 2
	s_add_u32 s10, s10, 0x100
	s_addc_u32 s11, s11, 0
	s_cmp_gt_u32 s96, 29
	s_cbranch_scc0 .LBB0_290
	s_and_b64 vcc, exec, s[56:57]
	s_cbranch_vccz .LBB0_293
	s_barrier

.LBB0_473:
	s_add_u32 s64, s56, s10
	s_addc_u32 s65, s57, s11
	s_add_u32 s64, s64, 0x100
	s_addc_u32 s65, s65, 0
	s_add_u32 vcc_lo, s93, s10
	s_addc_u32 vcc_hi, s94, s11
	s_add_i32 s16, 0, 0x10000
	s_cmpk_eq_i32 s10, 0xf00
	s_cselect_b32 s67, s55, s65
	s_cselect_b32 s66, s95, s64
	s_cselect_b32 s65, s53, vcc_hi
	s_cselect_b32 s64, s96, vcc_lo
	s_add_i32 s24, 0, 0x14000
	v_add_u32_e32 v146, s16, v197
	v_add_u32_e32 v182, s24, v197
	ds_read_b128 v[134:137], v146
	ds_read_b128 v[138:141], v146 offset:1024
	ds_read_b128 v[142:145], v146 offset:2048
	ds_read_b128 v[146:149], v146 offset:3072
	ds_read_b128 v[150:153], v182
	ds_read_b128 v[174:177], v182 offset:1024
	ds_read_b128 v[178:181], v182 offset:2048
	ds_read_b128 v[182:185], v182 offset:3072
	v_lshl_add_u64 v[190:191], v[130:131], 0, s[10:11]
	s_add_i32 m0, s80, 0xc000
	ds_read_b128 v[186:189], v200
	ds_read_b128 v[202:205], v200 offset:1024
	ds_read_b128 v[206:209], v200 offset:2048
	ds_read_b128 v[210:213], v200 offset:3072
	ds_read_b128 v[214:217], v200 offset:4096
	ds_read_b128 v[218:221], v200 offset:5120
	ds_read_b128 v[222:225], v200 offset:6144
	ds_read_b128 v[226:229], v200 offset:7168
	global_load_lds_dwordx4 v[190:191], off
	v_lshl_add_u64 v[190:191], v[132:133], 0, s[10:11]
	s_add_i32 m0, s80, 0xe000
	s_nop 0
	global_load_lds_dwordx4 v[190:191], off
	s_waitcnt vmcnt(8)
	s_waitcnt lgkmcnt(0)
	s_barrier
	s_setprio 1

	v_mfma_f32_16x16x32_bf16 v[126:129], v[134:137], v[186:189], v[126:129]
	v_mfma_f32_16x16x32_bf16 v[122:125], v[142:145], v[186:189], v[122:125]
	v_mfma_f32_16x16x32_bf16 v[118:121], v[134:137], v[206:209], v[118:121]
	v_mfma_f32_16x16x32_bf16 v[114:117], v[142:145], v[206:209], v[114:117]
	v_mfma_f32_16x16x32_bf16 v[110:113], v[134:137], v[214:217], v[110:113]
	v_mfma_f32_16x16x32_bf16 v[106:109], v[142:145], v[214:217], v[106:109]
	v_mfma_f32_16x16x32_bf16 v[102:105], v[134:137], v[222:225], v[102:105]
	v_mfma_f32_16x16x32_bf16 v[98:101], v[142:145], v[222:225], v[98:101]
	v_mfma_f32_16x16x32_bf16 v[126:129], v[138:141], v[202:205], v[126:129]
	v_mfma_f32_16x16x32_bf16 v[122:125], v[146:149], v[202:205], v[122:125]
	v_mfma_f32_16x16x32_bf16 v[118:121], v[138:141], v[210:213], v[118:121]
	v_mfma_f32_16x16x32_bf16 v[114:117], v[146:149], v[210:213], v[114:117]
	v_mfma_f32_16x16x32_bf16 v[110:113], v[138:141], v[218:221], v[110:113]
	v_mfma_f32_16x16x32_bf16 v[106:109], v[146:149], v[218:221], v[106:109]
	v_mfma_f32_16x16x32_bf16 v[102:105], v[138:141], v[226:229], v[102:105]
	v_mfma_f32_16x16x32_bf16 v[98:101], v[146:149], v[226:229], v[98:101]
	s_setprio 0
	s_setprio 1
	v_mfma_f32_16x16x32_bf16 v[94:97], v[150:153], v[186:189], v[94:97]
	v_mfma_f32_16x16x32_bf16 v[90:93], v[178:181], v[186:189], v[90:93]
	v_mfma_f32_16x16x32_bf16 v[86:89], v[150:153], v[206:209], v[86:89]
	v_mfma_f32_16x16x32_bf16 v[82:85], v[178:181], v[206:209], v[82:85]
	v_mfma_f32_16x16x32_bf16 v[78:81], v[150:153], v[214:217], v[78:81]
	v_mfma_f32_16x16x32_bf16 v[74:77], v[178:181], v[214:217], v[74:77]
	v_mfma_f32_16x16x32_bf16 v[70:73], v[150:153], v[222:225], v[70:73]
	v_mfma_f32_16x16x32_bf16 v[66:69], v[178:181], v[222:225], v[66:69]
	v_mfma_f32_16x16x32_bf16 v[94:97], v[174:177], v[202:205], v[94:97]
	v_mfma_f32_16x16x32_bf16 v[90:93], v[182:185], v[202:205], v[90:93]
	v_mfma_f32_16x16x32_bf16 v[86:89], v[174:177], v[210:213], v[86:89]
	v_mfma_f32_16x16x32_bf16 v[82:85], v[182:185], v[210:213], v[82:85]
	v_mfma_f32_16x16x32_bf16 v[78:81], v[174:177], v[218:221], v[78:81]
	v_mfma_f32_16x16x32_bf16 v[74:77], v[182:185], v[218:221], v[74:77]
	v_mfma_f32_16x16x32_bf16 v[70:73], v[174:177], v[226:229], v[70:73]
	v_mfma_f32_16x16x32_bf16 v[66:69], v[182:185], v[226:229], v[66:69]
	s_setprio 0
	s_barrier
	s_add_i32 s16, s16, s30
	v_lshl_add_u64 v[190:191], s[64:65], 0, v[154:155]
	s_mov_b32 m0, s16
	ds_read_b128 v[186:189], v200 offset:16384
	ds_read_b128 v[202:205], v200 offset:17408
	ds_read_b128 v[206:209], v200 offset:18432
	ds_read_b128 v[210:213], v200 offset:19456
	ds_read_b128 v[214:217], v200 offset:20480
	ds_read_b128 v[218:221], v200 offset:21504
	ds_read_b128 v[222:225], v200 offset:22528
	ds_read_b128 v[226:229], v200 offset:23552
	global_load_lds_dwordx4 v[190:191], off
	s_add_i32 m0, s16, 0x2000
	s_add_u32 vcc_lo, s64, 0x80000
	v_lshl_add_u64 v[230:231], s[64:65], 0, v[164:165]
	s_addc_u32 vcc_hi, s65, 0
	s_add_i32 s16, s24, s30
	global_load_lds_dwordx4 v[230:231], off
	v_lshl_add_u64 v[232:233], vcc, 0, v[154:155]
	s_mov_b32 m0, s16
	v_lshl_add_u64 v[234:235], s[66:67], 0, v[166:167]
	global_load_lds_dwordx4 v[232:233], off
	v_lshl_add_u64 v[232:233], vcc, 0, v[164:165]
	s_add_i32 m0, s16, 0x2000
	s_nop 0
	global_load_lds_dwordx4 v[232:233], off
	v_lshl_add_u64 v[232:233], s[66:67], 0, v[168:169]
	s_mov_b32 m0, s80
	s_nop 0
	global_load_lds_dwordx4 v[232:233], off
	s_mov_b32 m0, s81
	s_nop 0
	global_load_lds_dwordx4 v[234:235], off
	s_waitcnt vmcnt(8)
	s_waitcnt lgkmcnt(0)
	s_barrier
	s_setprio 1

	v_mfma_f32_16x16x32_bf16 v[62:65], v[134:137], v[186:189], v[62:65]
	v_mfma_f32_16x16x32_bf16 v[58:61], v[142:145], v[186:189], v[58:61]
	v_mfma_f32_16x16x32_bf16 v[54:57], v[134:137], v[206:209], v[54:57]
	v_mfma_f32_16x16x32_bf16 v[50:53], v[142:145], v[206:209], v[50:53]
	v_mfma_f32_16x16x32_bf16 v[46:49], v[134:137], v[214:217], v[46:49]
	v_mfma_f32_16x16x32_bf16 v[42:45], v[142:145], v[214:217], v[42:45]
	v_mfma_f32_16x16x32_bf16 v[38:41], v[134:137], v[222:225], v[38:41]
	v_mfma_f32_16x16x32_bf16 v[34:37], v[142:145], v[222:225], v[34:37]
	v_mfma_f32_16x16x32_bf16 v[62:65], v[138:141], v[202:205], v[62:65]
	v_mfma_f32_16x16x32_bf16 v[58:61], v[146:149], v[202:205], v[58:61]
	v_mfma_f32_16x16x32_bf16 v[54:57], v[138:141], v[210:213], v[54:57]
	v_mfma_f32_16x16x32_bf16 v[50:53], v[146:149], v[210:213], v[50:53]
	v_mfma_f32_16x16x32_bf16 v[46:49], v[138:141], v[218:221], v[46:49]
	v_mfma_f32_16x16x32_bf16 v[42:45], v[146:149], v[218:221], v[42:45]
	v_mfma_f32_16x16x32_bf16 v[38:41], v[138:141], v[226:229], v[38:41]
	v_mfma_f32_16x16x32_bf16 v[34:37], v[146:149], v[226:229], v[34:37]
	s_setprio 0
	s_setprio 1
	v_mfma_f32_16x16x32_bf16 v[30:33], v[150:153], v[186:189], v[30:33]
	v_mfma_f32_16x16x32_bf16 v[26:29], v[178:181], v[186:189], v[26:29]
	v_mfma_f32_16x16x32_bf16 v[22:25], v[150:153], v[206:209], v[22:25]
	v_mfma_f32_16x16x32_bf16 v[18:21], v[178:181], v[206:209], v[18:21]
	v_mfma_f32_16x16x32_bf16 v[14:17], v[150:153], v[214:217], v[14:17]
	v_mfma_f32_16x16x32_bf16 v[10:13], v[178:181], v[214:217], v[10:13]
	v_mfma_f32_16x16x32_bf16 v[6:9], v[150:153], v[222:225], v[6:9]
	v_mfma_f32_16x16x32_bf16 v[2:5], v[178:181], v[222:225], v[2:5]
	v_mfma_f32_16x16x32_bf16 v[30:33], v[174:177], v[202:205], v[30:33]
	v_mfma_f32_16x16x32_bf16 v[26:29], v[182:185], v[202:205], v[26:29]
	v_mfma_f32_16x16x32_bf16 v[22:25], v[174:177], v[210:213], v[22:25]
	v_mfma_f32_16x16x32_bf16 v[18:21], v[182:185], v[210:213], v[18:21]
	v_mfma_f32_16x16x32_bf16 v[14:17], v[174:177], v[218:221], v[14:17]
	v_mfma_f32_16x16x32_bf16 v[10:13], v[182:185], v[218:221], v[10:13]
	v_mfma_f32_16x16x32_bf16 v[6:9], v[174:177], v[226:229], v[6:9]
	v_mfma_f32_16x16x32_bf16 v[2:5], v[182:185], v[226:229], v[2:5]
	s_setprio 0
	s_barrier
	s_add_i32 s16, 0, 0x18000
	s_add_i32 s24, 0, 0x1c000
	v_add_u32_e32 v146, s16, v197
	v_add_u32_e32 v182, s24, v197
	ds_read_b128 v[134:137], v146
	ds_read_b128 v[138:141], v146 offset:1024
	ds_read_b128 v[142:145], v146 offset:2048
	ds_read_b128 v[146:149], v146 offset:3072
	ds_read_b128 v[150:153], v182
	ds_read_b128 v[174:177], v182 offset:1024
	ds_read_b128 v[178:181], v182 offset:2048
	ds_read_b128 v[182:185], v182 offset:3072
	s_add_u32 s66, s66, 0x80000
	s_addc_u32 s67, s67, 0
	s_mov_b32 m0, s82
	v_lshl_add_u64 v[236:237], s[66:67], 0, v[168:169]
	ds_read_b128 v[186:189], v200 offset:32768
	ds_read_b128 v[202:205], v200 offset:33792
	ds_read_b128 v[206:209], v200 offset:34816
	ds_read_b128 v[210:213], v200 offset:35840
	ds_read_b128 v[214:217], v200 offset:36864
	ds_read_b128 v[218:221], v200 offset:37888
	ds_read_b128 v[222:225], v200 offset:38912
	ds_read_b128 v[226:229], v200 offset:39936
	global_load_lds_dwordx4 v[236:237], off
	v_lshl_add_u64 v[236:237], s[66:67], 0, v[166:167]
	s_mov_b32 m0, s83
	s_nop 0
	global_load_lds_dwordx4 v[236:237], off
	s_waitcnt vmcnt(8)
	s_waitcnt lgkmcnt(0)
	s_barrier
	s_setprio 1

	v_mfma_f32_16x16x32_bf16 v[126:129], v[134:137], v[186:189], v[126:129]
	v_mfma_f32_16x16x32_bf16 v[122:125], v[142:145], v[186:189], v[122:125]
	v_mfma_f32_16x16x32_bf16 v[118:121], v[134:137], v[206:209], v[118:121]
	v_mfma_f32_16x16x32_bf16 v[114:117], v[142:145], v[206:209], v[114:117]
	v_mfma_f32_16x16x32_bf16 v[110:113], v[134:137], v[214:217], v[110:113]
	v_mfma_f32_16x16x32_bf16 v[106:109], v[142:145], v[214:217], v[106:109]
	v_mfma_f32_16x16x32_bf16 v[102:105], v[134:137], v[222:225], v[102:105]
	v_mfma_f32_16x16x32_bf16 v[98:101], v[142:145], v[222:225], v[98:101]
	v_mfma_f32_16x16x32_bf16 v[126:129], v[138:141], v[202:205], v[126:129]
	v_mfma_f32_16x16x32_bf16 v[122:125], v[146:149], v[202:205], v[122:125]
	v_mfma_f32_16x16x32_bf16 v[118:121], v[138:141], v[210:213], v[118:121]
	v_mfma_f32_16x16x32_bf16 v[114:117], v[146:149], v[210:213], v[114:117]
	v_mfma_f32_16x16x32_bf16 v[110:113], v[138:141], v[218:221], v[110:113]
	v_mfma_f32_16x16x32_bf16 v[106:109], v[146:149], v[218:221], v[106:109]
	v_mfma_f32_16x16x32_bf16 v[102:105], v[138:141], v[226:229], v[102:105]
	v_mfma_f32_16x16x32_bf16 v[98:101], v[146:149], v[226:229], v[98:101]
	s_setprio 0
	s_setprio 1
	v_mfma_f32_16x16x32_bf16 v[94:97], v[150:153], v[186:189], v[94:97]
	v_mfma_f32_16x16x32_bf16 v[90:93], v[178:181], v[186:189], v[90:93]
	v_mfma_f32_16x16x32_bf16 v[86:89], v[150:153], v[206:209], v[86:89]
	v_mfma_f32_16x16x32_bf16 v[82:85], v[178:181], v[206:209], v[82:85]
	v_mfma_f32_16x16x32_bf16 v[78:81], v[150:153], v[214:217], v[78:81]
	v_mfma_f32_16x16x32_bf16 v[74:77], v[178:181], v[214:217], v[74:77]
	v_mfma_f32_16x16x32_bf16 v[70:73], v[150:153], v[222:225], v[70:73]
	v_mfma_f32_16x16x32_bf16 v[66:69], v[178:181], v[222:225], v[66:69]
	v_mfma_f32_16x16x32_bf16 v[94:97], v[174:177], v[202:205], v[94:97]
	v_mfma_f32_16x16x32_bf16 v[90:93], v[182:185], v[202:205], v[90:93]
	v_mfma_f32_16x16x32_bf16 v[86:89], v[174:177], v[210:213], v[86:89]
	v_mfma_f32_16x16x32_bf16 v[82:85], v[182:185], v[210:213], v[82:85]
	v_mfma_f32_16x16x32_bf16 v[78:81], v[174:177], v[218:221], v[78:81]
	v_mfma_f32_16x16x32_bf16 v[74:77], v[182:185], v[218:221], v[74:77]
	v_mfma_f32_16x16x32_bf16 v[70:73], v[174:177], v[226:229], v[70:73]
	v_mfma_f32_16x16x32_bf16 v[66:69], v[182:185], v[226:229], v[66:69]
	s_setprio 0
	s_barrier
	s_add_i32 s16, s16, s30
	v_lshl_add_u64 v[190:191], v[190:191], 0, s[34:35]
	s_mov_b32 m0, s16
	ds_read_b128 v[186:189], v200 offset:49152
	ds_read_b128 v[202:205], v200 offset:50176
	ds_read_b128 v[206:209], v200 offset:51200
	ds_read_b128 v[210:213], v200 offset:52224
	ds_read_b128 v[214:217], v200 offset:53248
	ds_read_b128 v[218:221], v200 offset:54272
	ds_read_b128 v[222:225], v200 offset:55296
	ds_read_b128 v[226:229], v200 offset:56320
	global_load_lds_dwordx4 v[190:191], off
	s_add_i32 m0, s16, 0x2000
	s_add_u32 s64, s64, 0x80080
	v_lshl_add_u64 v[190:191], v[230:231], 0, s[34:35]
	s_addc_u32 s65, s65, 0
	s_add_i32 s16, s24, s30
	global_load_lds_dwordx4 v[190:191], off
	v_lshl_add_u64 v[190:191], s[64:65], 0, v[154:155]
	s_mov_b32 m0, s16
	s_nop 0
	global_load_lds_dwordx4 v[190:191], off
	v_lshl_add_u64 v[190:191], s[64:65], 0, v[164:165]
	s_add_i32 m0, s16, 0x2000
	s_nop 0
	global_load_lds_dwordx4 v[190:191], off
	v_lshl_add_u64 v[190:191], v[232:233], 0, s[34:35]
	s_mov_b32 m0, s84
	s_nop 0
	global_load_lds_dwordx4 v[190:191], off
	v_lshl_add_u64 v[190:191], v[234:235], 0, s[34:35]
	s_mov_b32 m0, s85
	s_nop 0
	global_load_lds_dwordx4 v[190:191], off
	s_waitcnt vmcnt(8)
	s_waitcnt lgkmcnt(0)
	s_barrier
	s_setprio 1

	v_mfma_f32_16x16x32_bf16 v[62:65], v[134:137], v[186:189], v[62:65]
	v_mfma_f32_16x16x32_bf16 v[58:61], v[142:145], v[186:189], v[58:61]
	v_mfma_f32_16x16x32_bf16 v[54:57], v[134:137], v[206:209], v[54:57]
	v_mfma_f32_16x16x32_bf16 v[50:53], v[142:145], v[206:209], v[50:53]
	v_mfma_f32_16x16x32_bf16 v[46:49], v[134:137], v[214:217], v[46:49]
	v_mfma_f32_16x16x32_bf16 v[42:45], v[142:145], v[214:217], v[42:45]
	v_mfma_f32_16x16x32_bf16 v[38:41], v[134:137], v[222:225], v[38:41]
	v_mfma_f32_16x16x32_bf16 v[34:37], v[142:145], v[222:225], v[34:37]
	v_mfma_f32_16x16x32_bf16 v[62:65], v[138:141], v[202:205], v[62:65]
	v_mfma_f32_16x16x32_bf16 v[58:61], v[146:149], v[202:205], v[58:61]
	v_mfma_f32_16x16x32_bf16 v[54:57], v[138:141], v[210:213], v[54:57]
	v_mfma_f32_16x16x32_bf16 v[50:53], v[146:149], v[210:213], v[50:53]
	v_mfma_f32_16x16x32_bf16 v[46:49], v[138:141], v[218:221], v[46:49]
	v_mfma_f32_16x16x32_bf16 v[42:45], v[146:149], v[218:221], v[42:45]
	v_mfma_f32_16x16x32_bf16 v[38:41], v[138:141], v[226:229], v[38:41]
	v_mfma_f32_16x16x32_bf16 v[34:37], v[146:149], v[226:229], v[34:37]
	s_setprio 0
	s_setprio 1
	v_mfma_f32_16x16x32_bf16 v[30:33], v[150:153], v[186:189], v[30:33]
	v_mfma_f32_16x16x32_bf16 v[26:29], v[178:181], v[186:189], v[26:29]
	v_mfma_f32_16x16x32_bf16 v[22:25], v[150:153], v[206:209], v[22:25]
	v_mfma_f32_16x16x32_bf16 v[18:21], v[178:181], v[206:209], v[18:21]
	v_mfma_f32_16x16x32_bf16 v[14:17], v[150:153], v[214:217], v[14:17]
	v_mfma_f32_16x16x32_bf16 v[10:13], v[178:181], v[214:217], v[10:13]
	v_mfma_f32_16x16x32_bf16 v[6:9], v[150:153], v[222:225], v[6:9]
	v_mfma_f32_16x16x32_bf16 v[2:5], v[178:181], v[222:225], v[2:5]
	v_mfma_f32_16x16x32_bf16 v[30:33], v[174:177], v[202:205], v[30:33]
	v_mfma_f32_16x16x32_bf16 v[26:29], v[182:185], v[202:205], v[26:29]
	v_mfma_f32_16x16x32_bf16 v[22:25], v[174:177], v[210:213], v[22:25]
	v_mfma_f32_16x16x32_bf16 v[18:21], v[182:185], v[210:213], v[18:21]
	v_mfma_f32_16x16x32_bf16 v[14:17], v[174:177], v[218:221], v[14:17]
	v_mfma_f32_16x16x32_bf16 v[10:13], v[182:185], v[218:221], v[10:13]
	v_mfma_f32_16x16x32_bf16 v[6:9], v[174:177], v[226:229], v[6:9]
	v_mfma_f32_16x16x32_bf16 v[2:5], v[182:185], v[226:229], v[2:5]
	s_setprio 0
	s_barrier
	s_add_i32 s97, s97, 2
	s_add_u32 s10, s10, 0x100
	s_addc_u32 s11, s11, 0
	s_cmp_gt_u32 s97, 29
	s_cbranch_scc0 .LBB0_473
	s_and_b64 vcc, exec, s[46:47]
	s_cbranch_vccz .LBB0_476
	s_barrier

.LBB0_623:
	s_add_u32 s8, s52, s0
	s_addc_u32 s9, s53, s1
	s_add_u32 s8, s8, 0x100
	s_addc_u32 s9, s9, 0
	s_add_u32 s55, s76, s0
	s_addc_u32 s78, s77, s1
	s_add_i32 s79, 0, 0x10000
	s_cmpk_eq_i32 s0, 0xf00
	s_cselect_b32 s11, s12, s9
	s_cselect_b32 s10, s13, s8
	s_cselect_b32 s9, s26, s78
	s_cselect_b32 s8, s27, s55
	s_add_i32 s55, 0, 0x14000
	v_add_u32_e32 v148, s79, v204
	v_add_u32_e32 v186, s55, v204
	ds_read_b128 v[136:139], v148
	ds_read_b128 v[140:143], v148 offset:1024
	ds_read_b128 v[144:147], v148 offset:2048
	ds_read_b128 v[148:151], v148 offset:3072
	ds_read_b128 v[152:155], v186
	ds_read_b128 v[156:159], v186 offset:1024
	ds_read_b128 v[160:163], v186 offset:2048
	ds_read_b128 v[186:189], v186 offset:3072
	v_lshl_add_u64 v[230:231], v[132:133], 0, s[0:1]
	s_add_i32 m0, s25, 0xc000
	ds_read_b128 v[190:193], v205
	ds_read_b128 v[194:197], v205 offset:1024
	ds_read_b128 v[206:209], v205 offset:2048
	ds_read_b128 v[210:213], v205 offset:3072
	ds_read_b128 v[214:217], v205 offset:4096
	ds_read_b128 v[218:221], v205 offset:5120
	ds_read_b128 v[222:225], v205 offset:6144
	ds_read_b128 v[226:229], v205 offset:7168
	global_load_lds_dwordx4 v[230:231], off
	v_lshl_add_u64 v[230:231], v[134:135], 0, s[0:1]
	s_add_i32 m0, s25, 0xe000
	s_nop 0
	global_load_lds_dwordx4 v[230:231], off
	s_waitcnt vmcnt(8)
	s_waitcnt lgkmcnt(0)
	s_barrier
	s_setprio 1

	v_mfma_f32_16x16x32_bf16 v[128:131], v[136:139], v[190:193], v[128:131]
	v_mfma_f32_16x16x32_bf16 v[124:127], v[144:147], v[190:193], v[124:127]
	v_mfma_f32_16x16x32_bf16 v[120:123], v[136:139], v[206:209], v[120:123]
	v_mfma_f32_16x16x32_bf16 v[116:119], v[144:147], v[206:209], v[116:119]
	v_mfma_f32_16x16x32_bf16 v[112:115], v[136:139], v[214:217], v[112:115]
	v_mfma_f32_16x16x32_bf16 v[108:111], v[144:147], v[214:217], v[108:111]
	v_mfma_f32_16x16x32_bf16 v[104:107], v[136:139], v[222:225], v[104:107]
	v_mfma_f32_16x16x32_bf16 v[100:103], v[144:147], v[222:225], v[100:103]
	v_mfma_f32_16x16x32_bf16 v[128:131], v[140:143], v[194:197], v[128:131]
	v_mfma_f32_16x16x32_bf16 v[124:127], v[148:151], v[194:197], v[124:127]
	v_mfma_f32_16x16x32_bf16 v[120:123], v[140:143], v[210:213], v[120:123]
	v_mfma_f32_16x16x32_bf16 v[116:119], v[148:151], v[210:213], v[116:119]
	v_mfma_f32_16x16x32_bf16 v[112:115], v[140:143], v[218:221], v[112:115]
	v_mfma_f32_16x16x32_bf16 v[108:111], v[148:151], v[218:221], v[108:111]
	v_mfma_f32_16x16x32_bf16 v[104:107], v[140:143], v[226:229], v[104:107]
	v_mfma_f32_16x16x32_bf16 v[100:103], v[148:151], v[226:229], v[100:103]
	s_setprio 0
	s_setprio 1
	v_mfma_f32_16x16x32_bf16 v[96:99], v[152:155], v[190:193], v[96:99]
	v_mfma_f32_16x16x32_bf16 v[92:95], v[160:163], v[190:193], v[92:95]
	v_mfma_f32_16x16x32_bf16 v[88:91], v[152:155], v[206:209], v[88:91]
	v_mfma_f32_16x16x32_bf16 v[84:87], v[160:163], v[206:209], v[84:87]
	v_mfma_f32_16x16x32_bf16 v[80:83], v[152:155], v[214:217], v[80:83]
	v_mfma_f32_16x16x32_bf16 v[76:79], v[160:163], v[214:217], v[76:79]
	v_mfma_f32_16x16x32_bf16 v[72:75], v[152:155], v[222:225], v[72:75]
	v_mfma_f32_16x16x32_bf16 v[68:71], v[160:163], v[222:225], v[68:71]
	v_mfma_f32_16x16x32_bf16 v[96:99], v[156:159], v[194:197], v[96:99]
	v_mfma_f32_16x16x32_bf16 v[92:95], v[186:189], v[194:197], v[92:95]
	v_mfma_f32_16x16x32_bf16 v[88:91], v[156:159], v[210:213], v[88:91]
	v_mfma_f32_16x16x32_bf16 v[84:87], v[186:189], v[210:213], v[84:87]
	v_mfma_f32_16x16x32_bf16 v[80:83], v[156:159], v[218:221], v[80:83]
	v_mfma_f32_16x16x32_bf16 v[76:79], v[186:189], v[218:221], v[76:79]
	v_mfma_f32_16x16x32_bf16 v[72:75], v[156:159], v[226:229], v[72:75]
	v_mfma_f32_16x16x32_bf16 v[68:71], v[186:189], v[226:229], v[68:71]
	s_setprio 0
	s_barrier
	s_add_i32 s78, s79, s24
	v_lshl_add_u64 v[230:231], s[8:9], 0, v[170:171]
	s_mov_b32 m0, s78
	ds_read_b128 v[190:193], v205 offset:16384
	ds_read_b128 v[194:197], v205 offset:17408
	ds_read_b128 v[206:209], v205 offset:18432
	ds_read_b128 v[210:213], v205 offset:19456
	ds_read_b128 v[214:217], v205 offset:20480
	ds_read_b128 v[218:221], v205 offset:21504
	ds_read_b128 v[222:225], v205 offset:22528
	ds_read_b128 v[226:229], v205 offset:23552
	global_load_lds_dwordx4 v[230:231], off
	s_add_i32 m0, s78, 0x2000
	s_add_u32 s78, s8, 0x80000
	v_lshl_add_u64 v[232:233], s[8:9], 0, v[174:175]
	s_addc_u32 s79, s9, 0
	s_add_i32 s55, s55, s24
	global_load_lds_dwordx4 v[232:233], off
	v_lshl_add_u64 v[234:235], s[78:79], 0, v[170:171]
	s_mov_b32 m0, s55
	v_lshl_add_u64 v[236:237], s[10:11], 0, v[172:173]
	global_load_lds_dwordx4 v[234:235], off
	v_lshl_add_u64 v[234:235], s[78:79], 0, v[174:175]
	s_add_i32 m0, s55, 0x2000
	s_nop 0
	global_load_lds_dwordx4 v[234:235], off
	v_lshl_add_u64 v[234:235], s[10:11], 0, v[168:169]
	s_mov_b32 m0, s25
	s_nop 0
	global_load_lds_dwordx4 v[234:235], off
	s_mov_b32 m0, s30
	s_nop 0
	global_load_lds_dwordx4 v[236:237], off
	s_waitcnt vmcnt(8)
	s_waitcnt lgkmcnt(0)
	s_barrier
	s_setprio 1

	v_mfma_f32_16x16x32_bf16 v[64:67], v[136:139], v[190:193], v[64:67]
	v_mfma_f32_16x16x32_bf16 v[60:63], v[144:147], v[190:193], v[60:63]
	v_mfma_f32_16x16x32_bf16 v[56:59], v[136:139], v[206:209], v[56:59]
	v_mfma_f32_16x16x32_bf16 v[52:55], v[144:147], v[206:209], v[52:55]
	v_mfma_f32_16x16x32_bf16 v[48:51], v[136:139], v[214:217], v[48:51]
	v_mfma_f32_16x16x32_bf16 v[44:47], v[144:147], v[214:217], v[44:47]
	v_mfma_f32_16x16x32_bf16 v[40:43], v[136:139], v[222:225], v[40:43]
	v_mfma_f32_16x16x32_bf16 v[36:39], v[144:147], v[222:225], v[36:39]
	v_mfma_f32_16x16x32_bf16 v[64:67], v[140:143], v[194:197], v[64:67]
	v_mfma_f32_16x16x32_bf16 v[60:63], v[148:151], v[194:197], v[60:63]
	v_mfma_f32_16x16x32_bf16 v[56:59], v[140:143], v[210:213], v[56:59]
	v_mfma_f32_16x16x32_bf16 v[52:55], v[148:151], v[210:213], v[52:55]
	v_mfma_f32_16x16x32_bf16 v[48:51], v[140:143], v[218:221], v[48:51]
	v_mfma_f32_16x16x32_bf16 v[44:47], v[148:151], v[218:221], v[44:47]
	v_mfma_f32_16x16x32_bf16 v[40:43], v[140:143], v[226:229], v[40:43]
	v_mfma_f32_16x16x32_bf16 v[36:39], v[148:151], v[226:229], v[36:39]
	s_setprio 0
	s_setprio 1
	v_mfma_f32_16x16x32_bf16 v[32:35], v[152:155], v[190:193], v[32:35]
	v_mfma_f32_16x16x32_bf16 v[28:31], v[160:163], v[190:193], v[28:31]
	v_mfma_f32_16x16x32_bf16 v[24:27], v[152:155], v[206:209], v[24:27]
	v_mfma_f32_16x16x32_bf16 v[20:23], v[160:163], v[206:209], v[20:23]
	v_mfma_f32_16x16x32_bf16 v[16:19], v[152:155], v[214:217], v[16:19]
	v_mfma_f32_16x16x32_bf16 v[12:15], v[160:163], v[214:217], v[12:15]
	v_mfma_f32_16x16x32_bf16 v[8:11], v[152:155], v[222:225], v[8:11]
	v_mfma_f32_16x16x32_bf16 v[4:7], v[160:163], v[222:225], v[4:7]
	v_mfma_f32_16x16x32_bf16 v[32:35], v[156:159], v[194:197], v[32:35]
	v_mfma_f32_16x16x32_bf16 v[28:31], v[186:189], v[194:197], v[28:31]
	v_mfma_f32_16x16x32_bf16 v[24:27], v[156:159], v[210:213], v[24:27]
	v_mfma_f32_16x16x32_bf16 v[20:23], v[186:189], v[210:213], v[20:23]
	v_mfma_f32_16x16x32_bf16 v[16:19], v[156:159], v[218:221], v[16:19]
	v_mfma_f32_16x16x32_bf16 v[12:15], v[186:189], v[218:221], v[12:15]
	v_mfma_f32_16x16x32_bf16 v[8:11], v[156:159], v[226:229], v[8:11]
	v_mfma_f32_16x16x32_bf16 v[4:7], v[186:189], v[226:229], v[4:7]
	s_setprio 0
	s_barrier
	s_add_i32 s55, 0, 0x18000
	s_add_i32 s78, 0, 0x1c000
	v_add_u32_e32 v148, s55, v204
	v_add_u32_e32 v186, s78, v204
	ds_read_b128 v[136:139], v148
	ds_read_b128 v[140:143], v148 offset:1024
	ds_read_b128 v[144:147], v148 offset:2048
	ds_read_b128 v[148:151], v148 offset:3072
	ds_read_b128 v[152:155], v186
	ds_read_b128 v[156:159], v186 offset:1024
	ds_read_b128 v[160:163], v186 offset:2048
	ds_read_b128 v[186:189], v186 offset:3072
	s_add_u32 s10, s10, 0x80000
	s_addc_u32 s11, s11, 0
	s_mov_b32 m0, s31
	v_lshl_add_u64 v[238:239], s[10:11], 0, v[168:169]
	ds_read_b128 v[190:193], v205 offset:32768
	ds_read_b128 v[194:197], v205 offset:33792
	ds_read_b128 v[206:209], v205 offset:34816
	ds_read_b128 v[210:213], v205 offset:35840
	ds_read_b128 v[214:217], v205 offset:36864
	ds_read_b128 v[218:221], v205 offset:37888
	ds_read_b128 v[222:225], v205 offset:38912
	ds_read_b128 v[226:229], v205 offset:39936
	global_load_lds_dwordx4 v[238:239], off
	v_lshl_add_u64 v[238:239], s[10:11], 0, v[172:173]
	s_mov_b32 m0, s36
	s_nop 0
	global_load_lds_dwordx4 v[238:239], off
	s_waitcnt vmcnt(8)
	s_waitcnt lgkmcnt(0)
	s_barrier
	s_setprio 1

	v_mfma_f32_16x16x32_bf16 v[128:131], v[136:139], v[190:193], v[128:131]
	v_mfma_f32_16x16x32_bf16 v[124:127], v[144:147], v[190:193], v[124:127]
	v_mfma_f32_16x16x32_bf16 v[120:123], v[136:139], v[206:209], v[120:123]
	v_mfma_f32_16x16x32_bf16 v[116:119], v[144:147], v[206:209], v[116:119]
	v_mfma_f32_16x16x32_bf16 v[112:115], v[136:139], v[214:217], v[112:115]
	v_mfma_f32_16x16x32_bf16 v[108:111], v[144:147], v[214:217], v[108:111]
	v_mfma_f32_16x16x32_bf16 v[104:107], v[136:139], v[222:225], v[104:107]
	v_mfma_f32_16x16x32_bf16 v[100:103], v[144:147], v[222:225], v[100:103]
	v_mfma_f32_16x16x32_bf16 v[128:131], v[140:143], v[194:197], v[128:131]
	v_mfma_f32_16x16x32_bf16 v[124:127], v[148:151], v[194:197], v[124:127]
	v_mfma_f32_16x16x32_bf16 v[120:123], v[140:143], v[210:213], v[120:123]
	v_mfma_f32_16x16x32_bf16 v[116:119], v[148:151], v[210:213], v[116:119]
	v_mfma_f32_16x16x32_bf16 v[112:115], v[140:143], v[218:221], v[112:115]
	v_mfma_f32_16x16x32_bf16 v[108:111], v[148:151], v[218:221], v[108:111]
	v_mfma_f32_16x16x32_bf16 v[104:107], v[140:143], v[226:229], v[104:107]
	v_mfma_f32_16x16x32_bf16 v[100:103], v[148:151], v[226:229], v[100:103]
	s_setprio 0
	s_setprio 1
	v_mfma_f32_16x16x32_bf16 v[96:99], v[152:155], v[190:193], v[96:99]
	v_mfma_f32_16x16x32_bf16 v[92:95], v[160:163], v[190:193], v[92:95]
	v_mfma_f32_16x16x32_bf16 v[88:91], v[152:155], v[206:209], v[88:91]
	v_mfma_f32_16x16x32_bf16 v[84:87], v[160:163], v[206:209], v[84:87]
	v_mfma_f32_16x16x32_bf16 v[80:83], v[152:155], v[214:217], v[80:83]
	v_mfma_f32_16x16x32_bf16 v[76:79], v[160:163], v[214:217], v[76:79]
	v_mfma_f32_16x16x32_bf16 v[72:75], v[152:155], v[222:225], v[72:75]
	v_mfma_f32_16x16x32_bf16 v[68:71], v[160:163], v[222:225], v[68:71]
	v_mfma_f32_16x16x32_bf16 v[96:99], v[156:159], v[194:197], v[96:99]
	v_mfma_f32_16x16x32_bf16 v[92:95], v[186:189], v[194:197], v[92:95]
	v_mfma_f32_16x16x32_bf16 v[88:91], v[156:159], v[210:213], v[88:91]
	v_mfma_f32_16x16x32_bf16 v[84:87], v[186:189], v[210:213], v[84:87]
	v_mfma_f32_16x16x32_bf16 v[80:83], v[156:159], v[218:221], v[80:83]
	v_mfma_f32_16x16x32_bf16 v[76:79], v[186:189], v[218:221], v[76:79]
	v_mfma_f32_16x16x32_bf16 v[72:75], v[156:159], v[226:229], v[72:75]
	v_mfma_f32_16x16x32_bf16 v[68:71], v[186:189], v[226:229], v[68:71]
	s_setprio 0
	s_barrier
	s_add_i32 s10, s55, s24
	v_lshl_add_u64 v[230:231], v[230:231], 0, s[28:29]
	s_mov_b32 m0, s10
	ds_read_b128 v[190:193], v205 offset:49152
	ds_read_b128 v[194:197], v205 offset:50176
	ds_read_b128 v[206:209], v205 offset:51200
	ds_read_b128 v[210:213], v205 offset:52224
	ds_read_b128 v[214:217], v205 offset:53248
	ds_read_b128 v[218:221], v205 offset:54272
	ds_read_b128 v[222:225], v205 offset:55296
	ds_read_b128 v[226:229], v205 offset:56320
	global_load_lds_dwordx4 v[230:231], off
	s_add_i32 m0, s10, 0x2000
	s_add_u32 s8, s8, 0x80080
	v_lshl_add_u64 v[230:231], v[232:233], 0, s[28:29]
	s_addc_u32 s9, s9, 0
	s_add_i32 s10, s78, s24
	global_load_lds_dwordx4 v[230:231], off
	v_lshl_add_u64 v[230:231], s[8:9], 0, v[170:171]
	s_mov_b32 m0, s10
	s_nop 0
	global_load_lds_dwordx4 v[230:231], off
	v_lshl_add_u64 v[230:231], s[8:9], 0, v[174:175]
	s_add_i32 m0, s10, 0x2000
	s_nop 0
	global_load_lds_dwordx4 v[230:231], off
	v_lshl_add_u64 v[230:231], v[234:235], 0, s[28:29]
	s_mov_b32 m0, s45
	s_nop 0
	global_load_lds_dwordx4 v[230:231], off
	v_lshl_add_u64 v[230:231], v[236:237], 0, s[28:29]
	s_mov_b32 m0, s60
	s_nop 0
	global_load_lds_dwordx4 v[230:231], off
	s_waitcnt vmcnt(8)
	s_waitcnt lgkmcnt(0)
	s_barrier
	s_setprio 1

	v_mfma_f32_16x16x32_bf16 v[64:67], v[136:139], v[190:193], v[64:67]
	v_mfma_f32_16x16x32_bf16 v[60:63], v[144:147], v[190:193], v[60:63]
	v_mfma_f32_16x16x32_bf16 v[56:59], v[136:139], v[206:209], v[56:59]
	v_mfma_f32_16x16x32_bf16 v[52:55], v[144:147], v[206:209], v[52:55]
	v_mfma_f32_16x16x32_bf16 v[48:51], v[136:139], v[214:217], v[48:51]
	v_mfma_f32_16x16x32_bf16 v[44:47], v[144:147], v[214:217], v[44:47]
	v_mfma_f32_16x16x32_bf16 v[40:43], v[136:139], v[222:225], v[40:43]
	v_mfma_f32_16x16x32_bf16 v[36:39], v[144:147], v[222:225], v[36:39]
	v_mfma_f32_16x16x32_bf16 v[64:67], v[140:143], v[194:197], v[64:67]
	v_mfma_f32_16x16x32_bf16 v[60:63], v[148:151], v[194:197], v[60:63]
	v_mfma_f32_16x16x32_bf16 v[56:59], v[140:143], v[210:213], v[56:59]
	v_mfma_f32_16x16x32_bf16 v[52:55], v[148:151], v[210:213], v[52:55]
	v_mfma_f32_16x16x32_bf16 v[48:51], v[140:143], v[218:221], v[48:51]
	v_mfma_f32_16x16x32_bf16 v[44:47], v[148:151], v[218:221], v[44:47]
	v_mfma_f32_16x16x32_bf16 v[40:43], v[140:143], v[226:229], v[40:43]
	v_mfma_f32_16x16x32_bf16 v[36:39], v[148:151], v[226:229], v[36:39]
	s_setprio 0
	s_setprio 1
	v_mfma_f32_16x16x32_bf16 v[32:35], v[152:155], v[190:193], v[32:35]
	v_mfma_f32_16x16x32_bf16 v[28:31], v[160:163], v[190:193], v[28:31]
	v_mfma_f32_16x16x32_bf16 v[24:27], v[152:155], v[206:209], v[24:27]
	v_mfma_f32_16x16x32_bf16 v[20:23], v[160:163], v[206:209], v[20:23]
	v_mfma_f32_16x16x32_bf16 v[16:19], v[152:155], v[214:217], v[16:19]
	v_mfma_f32_16x16x32_bf16 v[12:15], v[160:163], v[214:217], v[12:15]
	v_mfma_f32_16x16x32_bf16 v[8:11], v[152:155], v[222:225], v[8:11]
	v_mfma_f32_16x16x32_bf16 v[4:7], v[160:163], v[222:225], v[4:7]
	v_mfma_f32_16x16x32_bf16 v[32:35], v[156:159], v[194:197], v[32:35]
	v_mfma_f32_16x16x32_bf16 v[28:31], v[186:189], v[194:197], v[28:31]
	v_mfma_f32_16x16x32_bf16 v[24:27], v[156:159], v[210:213], v[24:27]
	v_mfma_f32_16x16x32_bf16 v[20:23], v[186:189], v[210:213], v[20:23]
	v_mfma_f32_16x16x32_bf16 v[16:19], v[156:159], v[218:221], v[16:19]
	v_mfma_f32_16x16x32_bf16 v[12:15], v[186:189], v[218:221], v[12:15]
	v_mfma_f32_16x16x32_bf16 v[8:11], v[156:159], v[226:229], v[8:11]
	v_mfma_f32_16x16x32_bf16 v[4:7], v[186:189], v[226:229], v[4:7]
	s_setprio 0
	s_barrier
	s_add_i32 s43, s43, 2
	s_add_u32 s0, s0, 0x100
	s_addc_u32 s1, s1, 0
	s_cmp_gt_u32 s43, 29
	s_cbranch_scc0 .LBB0_623
	s_and_b64 vcc, exec, s[50:51]
	s_cbranch_vccz .LBB0_626
	s_barrier

.LBB0_866:
	s_add_u32 s24, s34, s10
	s_addc_u32 s25, s35, s11
	s_add_u32 s24, s24, 0x100
	s_addc_u32 s25, s25, 0
	s_add_u32 s67, s60, s10
	s_addc_u32 s74, s61, s11
	s_add_i32 s75, 0, 0x10000
	s_cmpk_eq_i32 s10, 0xf00
	s_cselect_b32 s31, s27, s25
	s_cselect_b32 s30, s62, s24
	s_cselect_b32 s25, s15, s74
	s_cselect_b32 s24, s63, s67
	s_add_i32 s67, 0, 0x14000
	v_add_u32_e32 v148, s75, v189
	v_add_u32_e32 v178, s67, v189
	ds_read_b128 v[136:139], v148
	ds_read_b128 v[140:143], v148 offset:1024
	ds_read_b128 v[144:147], v148 offset:2048
	ds_read_b128 v[148:151], v148 offset:3072
	ds_read_b128 v[152:155], v178
	ds_read_b128 v[170:173], v178 offset:1024
	ds_read_b128 v[174:177], v178 offset:2048
	ds_read_b128 v[178:181], v178 offset:3072
	v_lshl_add_u64 v[186:187], v[132:133], 0, s[10:11]
	s_add_i32 m0, s48, 0xc000
	ds_read_b128 v[182:185], v191
	ds_read_b128 v[192:195], v191 offset:1024
	ds_read_b128 v[204:207], v191 offset:2048
	ds_read_b128 v[208:211], v191 offset:3072
	ds_read_b128 v[212:215], v191 offset:4096
	ds_read_b128 v[216:219], v191 offset:5120
	ds_read_b128 v[220:223], v191 offset:6144
	ds_read_b128 v[224:227], v191 offset:7168
	global_load_lds_dwordx4 v[186:187], off
	v_lshl_add_u64 v[186:187], v[134:135], 0, s[10:11]
	s_add_i32 m0, s48, 0xe000
	s_nop 0
	global_load_lds_dwordx4 v[186:187], off
	s_waitcnt vmcnt(8)
	s_waitcnt lgkmcnt(0)
	s_barrier
	s_setprio 1

	v_mfma_f32_16x16x32_bf16 v[128:131], v[136:139], v[182:185], v[128:131]
	v_mfma_f32_16x16x32_bf16 v[124:127], v[144:147], v[182:185], v[124:127]
	v_mfma_f32_16x16x32_bf16 v[120:123], v[136:139], v[204:207], v[120:123]
	v_mfma_f32_16x16x32_bf16 v[116:119], v[144:147], v[204:207], v[116:119]
	v_mfma_f32_16x16x32_bf16 v[112:115], v[136:139], v[212:215], v[112:115]
	v_mfma_f32_16x16x32_bf16 v[108:111], v[144:147], v[212:215], v[108:111]
	v_mfma_f32_16x16x32_bf16 v[104:107], v[136:139], v[220:223], v[104:107]
	v_mfma_f32_16x16x32_bf16 v[100:103], v[144:147], v[220:223], v[100:103]
	v_mfma_f32_16x16x32_bf16 v[128:131], v[140:143], v[192:195], v[128:131]
	v_mfma_f32_16x16x32_bf16 v[124:127], v[148:151], v[192:195], v[124:127]
	v_mfma_f32_16x16x32_bf16 v[120:123], v[140:143], v[208:211], v[120:123]
	v_mfma_f32_16x16x32_bf16 v[116:119], v[148:151], v[208:211], v[116:119]
	v_mfma_f32_16x16x32_bf16 v[112:115], v[140:143], v[216:219], v[112:115]
	v_mfma_f32_16x16x32_bf16 v[108:111], v[148:151], v[216:219], v[108:111]
	v_mfma_f32_16x16x32_bf16 v[104:107], v[140:143], v[224:227], v[104:107]
	v_mfma_f32_16x16x32_bf16 v[100:103], v[148:151], v[224:227], v[100:103]
	s_setprio 0
	s_setprio 1
	v_mfma_f32_16x16x32_bf16 v[96:99], v[152:155], v[182:185], v[96:99]
	v_mfma_f32_16x16x32_bf16 v[92:95], v[174:177], v[182:185], v[92:95]
	v_mfma_f32_16x16x32_bf16 v[88:91], v[152:155], v[204:207], v[88:91]
	v_mfma_f32_16x16x32_bf16 v[84:87], v[174:177], v[204:207], v[84:87]
	v_mfma_f32_16x16x32_bf16 v[80:83], v[152:155], v[212:215], v[80:83]
	v_mfma_f32_16x16x32_bf16 v[76:79], v[174:177], v[212:215], v[76:79]
	v_mfma_f32_16x16x32_bf16 v[72:75], v[152:155], v[220:223], v[72:75]
	v_mfma_f32_16x16x32_bf16 v[68:71], v[174:177], v[220:223], v[68:71]
	v_mfma_f32_16x16x32_bf16 v[96:99], v[170:173], v[192:195], v[96:99]
	v_mfma_f32_16x16x32_bf16 v[92:95], v[178:181], v[192:195], v[92:95]
	v_mfma_f32_16x16x32_bf16 v[88:91], v[170:173], v[208:211], v[88:91]
	v_mfma_f32_16x16x32_bf16 v[84:87], v[178:181], v[208:211], v[84:87]
	v_mfma_f32_16x16x32_bf16 v[80:83], v[170:173], v[216:219], v[80:83]
	v_mfma_f32_16x16x32_bf16 v[76:79], v[178:181], v[216:219], v[76:79]
	v_mfma_f32_16x16x32_bf16 v[72:75], v[170:173], v[224:227], v[72:75]
	v_mfma_f32_16x16x32_bf16 v[68:71], v[178:181], v[224:227], v[68:71]
	s_setprio 0
	s_barrier
	s_add_i32 s74, s75, s47
	v_lshl_add_u64 v[186:187], s[24:25], 0, v[2:3]
	s_mov_b32 m0, s74
	ds_read_b128 v[182:185], v191 offset:16384
	ds_read_b128 v[192:195], v191 offset:17408
	ds_read_b128 v[204:207], v191 offset:18432
	ds_read_b128 v[208:211], v191 offset:19456
	ds_read_b128 v[212:215], v191 offset:20480
	ds_read_b128 v[216:219], v191 offset:21504
	ds_read_b128 v[220:223], v191 offset:22528
	ds_read_b128 v[224:227], v191 offset:23552
	global_load_lds_dwordx4 v[186:187], off
	s_add_i32 m0, s74, 0x2000
	s_add_u32 s74, s24, 0x80000
	v_lshl_add_u64 v[196:197], s[24:25], 0, v[156:157]
	s_addc_u32 s75, s25, 0
	s_add_i32 s67, s67, s47
	global_load_lds_dwordx4 v[196:197], off
	v_lshl_add_u64 v[228:229], s[74:75], 0, v[2:3]
	s_mov_b32 m0, s67
	v_lshl_add_u64 v[230:231], s[30:31], 0, v[158:159]
	global_load_lds_dwordx4 v[228:229], off
	v_lshl_add_u64 v[228:229], s[74:75], 0, v[156:157]
	s_add_i32 m0, s67, 0x2000
	s_nop 0
	global_load_lds_dwordx4 v[228:229], off
	v_lshl_add_u64 v[228:229], s[30:31], 0, v[160:161]
	s_mov_b32 m0, s48
	s_nop 0
	global_load_lds_dwordx4 v[228:229], off
	s_mov_b32 m0, s49
	s_nop 0
	global_load_lds_dwordx4 v[230:231], off
	s_waitcnt vmcnt(8)
	s_waitcnt lgkmcnt(0)
	s_barrier
	s_setprio 1

	v_mfma_f32_16x16x32_bf16 v[64:67], v[136:139], v[182:185], v[64:67]
	v_mfma_f32_16x16x32_bf16 v[60:63], v[144:147], v[182:185], v[60:63]
	v_mfma_f32_16x16x32_bf16 v[56:59], v[136:139], v[204:207], v[56:59]
	v_mfma_f32_16x16x32_bf16 v[52:55], v[144:147], v[204:207], v[52:55]
	v_mfma_f32_16x16x32_bf16 v[48:51], v[136:139], v[212:215], v[48:51]
	v_mfma_f32_16x16x32_bf16 v[44:47], v[144:147], v[212:215], v[44:47]
	v_mfma_f32_16x16x32_bf16 v[40:43], v[136:139], v[220:223], v[40:43]
	v_mfma_f32_16x16x32_bf16 v[36:39], v[144:147], v[220:223], v[36:39]
	v_mfma_f32_16x16x32_bf16 v[64:67], v[140:143], v[192:195], v[64:67]
	v_mfma_f32_16x16x32_bf16 v[60:63], v[148:151], v[192:195], v[60:63]
	v_mfma_f32_16x16x32_bf16 v[56:59], v[140:143], v[208:211], v[56:59]
	v_mfma_f32_16x16x32_bf16 v[52:55], v[148:151], v[208:211], v[52:55]
	v_mfma_f32_16x16x32_bf16 v[48:51], v[140:143], v[216:219], v[48:51]
	v_mfma_f32_16x16x32_bf16 v[44:47], v[148:151], v[216:219], v[44:47]
	v_mfma_f32_16x16x32_bf16 v[40:43], v[140:143], v[224:227], v[40:43]
	v_mfma_f32_16x16x32_bf16 v[36:39], v[148:151], v[224:227], v[36:39]
	s_setprio 0
	s_setprio 1
	v_mfma_f32_16x16x32_bf16 v[32:35], v[152:155], v[182:185], v[32:35]
	v_mfma_f32_16x16x32_bf16 v[28:31], v[174:177], v[182:185], v[28:31]
	v_mfma_f32_16x16x32_bf16 v[24:27], v[152:155], v[204:207], v[24:27]
	v_mfma_f32_16x16x32_bf16 v[20:23], v[174:177], v[204:207], v[20:23]
	v_mfma_f32_16x16x32_bf16 v[16:19], v[152:155], v[212:215], v[16:19]
	v_mfma_f32_16x16x32_bf16 v[12:15], v[174:177], v[212:215], v[12:15]
	v_mfma_f32_16x16x32_bf16 v[8:11], v[152:155], v[220:223], v[8:11]
	v_mfma_f32_16x16x32_bf16 v[4:7], v[174:177], v[220:223], v[4:7]
	v_mfma_f32_16x16x32_bf16 v[32:35], v[170:173], v[192:195], v[32:35]
	v_mfma_f32_16x16x32_bf16 v[28:31], v[178:181], v[192:195], v[28:31]
	v_mfma_f32_16x16x32_bf16 v[24:27], v[170:173], v[208:211], v[24:27]
	v_mfma_f32_16x16x32_bf16 v[20:23], v[178:181], v[208:211], v[20:23]
	v_mfma_f32_16x16x32_bf16 v[16:19], v[170:173], v[216:219], v[16:19]
	v_mfma_f32_16x16x32_bf16 v[12:15], v[178:181], v[216:219], v[12:15]
	v_mfma_f32_16x16x32_bf16 v[8:11], v[170:173], v[224:227], v[8:11]
	v_mfma_f32_16x16x32_bf16 v[4:7], v[178:181], v[224:227], v[4:7]
	s_setprio 0
	s_barrier
	s_add_i32 s67, 0, 0x18000
	s_add_i32 s74, 0, 0x1c000
	v_add_u32_e32 v148, s67, v189
	v_add_u32_e32 v178, s74, v189
	ds_read_b128 v[136:139], v148
	ds_read_b128 v[140:143], v148 offset:1024
	ds_read_b128 v[144:147], v148 offset:2048
	ds_read_b128 v[148:151], v148 offset:3072
	ds_read_b128 v[152:155], v178
	ds_read_b128 v[170:173], v178 offset:1024
	ds_read_b128 v[174:177], v178 offset:2048
	ds_read_b128 v[178:181], v178 offset:3072
	s_add_u32 s30, s30, 0x80000
	s_addc_u32 s31, s31, 0
	s_mov_b32 m0, s50
	v_lshl_add_u64 v[232:233], s[30:31], 0, v[160:161]
	ds_read_b128 v[182:185], v191 offset:32768
	ds_read_b128 v[192:195], v191 offset:33792
	ds_read_b128 v[204:207], v191 offset:34816
	ds_read_b128 v[208:211], v191 offset:35840
	ds_read_b128 v[212:215], v191 offset:36864
	ds_read_b128 v[216:219], v191 offset:37888
	ds_read_b128 v[220:223], v191 offset:38912
	ds_read_b128 v[224:227], v191 offset:39936
	global_load_lds_dwordx4 v[232:233], off
	v_lshl_add_u64 v[232:233], s[30:31], 0, v[158:159]
	s_mov_b32 m0, s51
	s_nop 0
	global_load_lds_dwordx4 v[232:233], off
	s_waitcnt vmcnt(8)
	s_waitcnt lgkmcnt(0)
	s_barrier
	s_setprio 1

	v_mfma_f32_16x16x32_bf16 v[128:131], v[136:139], v[182:185], v[128:131]
	v_mfma_f32_16x16x32_bf16 v[124:127], v[144:147], v[182:185], v[124:127]
	v_mfma_f32_16x16x32_bf16 v[120:123], v[136:139], v[204:207], v[120:123]
	v_mfma_f32_16x16x32_bf16 v[116:119], v[144:147], v[204:207], v[116:119]
	v_mfma_f32_16x16x32_bf16 v[112:115], v[136:139], v[212:215], v[112:115]
	v_mfma_f32_16x16x32_bf16 v[108:111], v[144:147], v[212:215], v[108:111]
	v_mfma_f32_16x16x32_bf16 v[104:107], v[136:139], v[220:223], v[104:107]
	v_mfma_f32_16x16x32_bf16 v[100:103], v[144:147], v[220:223], v[100:103]
	v_mfma_f32_16x16x32_bf16 v[128:131], v[140:143], v[192:195], v[128:131]
	v_mfma_f32_16x16x32_bf16 v[124:127], v[148:151], v[192:195], v[124:127]
	v_mfma_f32_16x16x32_bf16 v[120:123], v[140:143], v[208:211], v[120:123]
	v_mfma_f32_16x16x32_bf16 v[116:119], v[148:151], v[208:211], v[116:119]
	v_mfma_f32_16x16x32_bf16 v[112:115], v[140:143], v[216:219], v[112:115]
	v_mfma_f32_16x16x32_bf16 v[108:111], v[148:151], v[216:219], v[108:111]
	v_mfma_f32_16x16x32_bf16 v[104:107], v[140:143], v[224:227], v[104:107]
	v_mfma_f32_16x16x32_bf16 v[100:103], v[148:151], v[224:227], v[100:103]
	s_setprio 0
	s_setprio 1
	v_mfma_f32_16x16x32_bf16 v[96:99], v[152:155], v[182:185], v[96:99]
	v_mfma_f32_16x16x32_bf16 v[92:95], v[174:177], v[182:185], v[92:95]
	v_mfma_f32_16x16x32_bf16 v[88:91], v[152:155], v[204:207], v[88:91]
	v_mfma_f32_16x16x32_bf16 v[84:87], v[174:177], v[204:207], v[84:87]
	v_mfma_f32_16x16x32_bf16 v[80:83], v[152:155], v[212:215], v[80:83]
	v_mfma_f32_16x16x32_bf16 v[76:79], v[174:177], v[212:215], v[76:79]
	v_mfma_f32_16x16x32_bf16 v[72:75], v[152:155], v[220:223], v[72:75]
	v_mfma_f32_16x16x32_bf16 v[68:71], v[174:177], v[220:223], v[68:71]
	v_mfma_f32_16x16x32_bf16 v[96:99], v[170:173], v[192:195], v[96:99]
	v_mfma_f32_16x16x32_bf16 v[92:95], v[178:181], v[192:195], v[92:95]
	v_mfma_f32_16x16x32_bf16 v[88:91], v[170:173], v[208:211], v[88:91]
	v_mfma_f32_16x16x32_bf16 v[84:87], v[178:181], v[208:211], v[84:87]
	v_mfma_f32_16x16x32_bf16 v[80:83], v[170:173], v[216:219], v[80:83]
	v_mfma_f32_16x16x32_bf16 v[76:79], v[178:181], v[216:219], v[76:79]
	v_mfma_f32_16x16x32_bf16 v[72:75], v[170:173], v[224:227], v[72:75]
	v_mfma_f32_16x16x32_bf16 v[68:71], v[178:181], v[224:227], v[68:71]
	s_setprio 0
	s_barrier
	s_add_i32 s30, s67, s47
	v_lshl_add_u64 v[186:187], v[186:187], 0, s[28:29]
	s_mov_b32 m0, s30
	ds_read_b128 v[182:185], v191 offset:49152
	ds_read_b128 v[192:195], v191 offset:50176
	ds_read_b128 v[204:207], v191 offset:51200
	ds_read_b128 v[208:211], v191 offset:52224
	ds_read_b128 v[212:215], v191 offset:53248
	ds_read_b128 v[216:219], v191 offset:54272
	ds_read_b128 v[220:223], v191 offset:55296
	ds_read_b128 v[224:227], v191 offset:56320
	global_load_lds_dwordx4 v[186:187], off
	s_add_i32 m0, s30, 0x2000
	s_add_u32 s24, s24, 0x80080
	v_lshl_add_u64 v[186:187], v[196:197], 0, s[28:29]
	s_addc_u32 s25, s25, 0
	s_add_i32 s30, s74, s47
	global_load_lds_dwordx4 v[186:187], off
	v_lshl_add_u64 v[186:187], s[24:25], 0, v[2:3]
	s_mov_b32 m0, s30
	s_nop 0
	global_load_lds_dwordx4 v[186:187], off
	v_lshl_add_u64 v[186:187], s[24:25], 0, v[156:157]
	s_add_i32 m0, s30, 0x2000
	s_nop 0
	global_load_lds_dwordx4 v[186:187], off
	v_lshl_add_u64 v[186:187], v[228:229], 0, s[28:29]
	s_mov_b32 m0, s52
	s_nop 0
	global_load_lds_dwordx4 v[186:187], off
	v_lshl_add_u64 v[186:187], v[230:231], 0, s[28:29]
	s_mov_b32 m0, s53
	s_nop 0
	global_load_lds_dwordx4 v[186:187], off
	s_waitcnt vmcnt(8)
	s_waitcnt lgkmcnt(0)
	s_barrier
	s_setprio 1

	v_mfma_f32_16x16x32_bf16 v[64:67], v[136:139], v[182:185], v[64:67]
	v_mfma_f32_16x16x32_bf16 v[60:63], v[144:147], v[182:185], v[60:63]
	v_mfma_f32_16x16x32_bf16 v[56:59], v[136:139], v[204:207], v[56:59]
	v_mfma_f32_16x16x32_bf16 v[52:55], v[144:147], v[204:207], v[52:55]
	v_mfma_f32_16x16x32_bf16 v[48:51], v[136:139], v[212:215], v[48:51]
	v_mfma_f32_16x16x32_bf16 v[44:47], v[144:147], v[212:215], v[44:47]
	v_mfma_f32_16x16x32_bf16 v[40:43], v[136:139], v[220:223], v[40:43]
	v_mfma_f32_16x16x32_bf16 v[36:39], v[144:147], v[220:223], v[36:39]
	v_mfma_f32_16x16x32_bf16 v[64:67], v[140:143], v[192:195], v[64:67]
	v_mfma_f32_16x16x32_bf16 v[60:63], v[148:151], v[192:195], v[60:63]
	v_mfma_f32_16x16x32_bf16 v[56:59], v[140:143], v[208:211], v[56:59]
	v_mfma_f32_16x16x32_bf16 v[52:55], v[148:151], v[208:211], v[52:55]
	v_mfma_f32_16x16x32_bf16 v[48:51], v[140:143], v[216:219], v[48:51]
	v_mfma_f32_16x16x32_bf16 v[44:47], v[148:151], v[216:219], v[44:47]
	v_mfma_f32_16x16x32_bf16 v[40:43], v[140:143], v[224:227], v[40:43]
	v_mfma_f32_16x16x32_bf16 v[36:39], v[148:151], v[224:227], v[36:39]
	s_setprio 0
	s_setprio 1
	v_mfma_f32_16x16x32_bf16 v[32:35], v[152:155], v[182:185], v[32:35]
	v_mfma_f32_16x16x32_bf16 v[28:31], v[174:177], v[182:185], v[28:31]
	v_mfma_f32_16x16x32_bf16 v[24:27], v[152:155], v[204:207], v[24:27]
	v_mfma_f32_16x16x32_bf16 v[20:23], v[174:177], v[204:207], v[20:23]
	v_mfma_f32_16x16x32_bf16 v[16:19], v[152:155], v[212:215], v[16:19]
	v_mfma_f32_16x16x32_bf16 v[12:15], v[174:177], v[212:215], v[12:15]
	v_mfma_f32_16x16x32_bf16 v[8:11], v[152:155], v[220:223], v[8:11]
	v_mfma_f32_16x16x32_bf16 v[4:7], v[174:177], v[220:223], v[4:7]
	v_mfma_f32_16x16x32_bf16 v[32:35], v[170:173], v[192:195], v[32:35]
	v_mfma_f32_16x16x32_bf16 v[28:31], v[178:181], v[192:195], v[28:31]
	v_mfma_f32_16x16x32_bf16 v[24:27], v[170:173], v[208:211], v[24:27]
	v_mfma_f32_16x16x32_bf16 v[20:23], v[178:181], v[208:211], v[20:23]
	v_mfma_f32_16x16x32_bf16 v[16:19], v[170:173], v[216:219], v[16:19]
	v_mfma_f32_16x16x32_bf16 v[12:15], v[178:181], v[216:219], v[12:15]
	v_mfma_f32_16x16x32_bf16 v[8:11], v[170:173], v[224:227], v[8:11]
	v_mfma_f32_16x16x32_bf16 v[4:7], v[178:181], v[224:227], v[4:7]
	s_setprio 0
	s_barrier
	s_add_i32 s66, s66, 2
	s_add_u32 s10, s10, 0x100
	s_addc_u32 s11, s11, 0
	s_cmp_gt_u32 s66, 29
	s_cbranch_scc0 .LBB0_866
	s_and_b64 vcc, exec, s[12:13]
	s_cbranch_vccz .LBB0_869
	s_barrier
